# row-rstd partial sums in the P1 and P5 epilogues reduced with packed f32 adds (4 ops instead of 7 per row block)
# speedup vs baseline: 1.0070x; 1.0014x over previous
; __device__ __forceinline__ float row_rstd(const float* ssp, int row, int fq) {
;     const f32x4 a = *(const f32x4*)(ssp + (size_t)row * 32 + 8 * fq), b = *(const f32x4*)(ssp + (size_t)row * 32 + 8 * fq + 4);
;     float s = ((a[0] + a[1]) + (a[2] + a[3])) + ((b[0] + b[1]) + (b[2] + b[3]));
;     s += __shfl_xor(s, 16); s += __shfl_xor(s, 32);
;     return __builtin_amdgcn_rsqf(s * (1.0f / 2048.0f) + 1e-6f);
;     __device__ __forceinline__ void operator()(f32x4 (&acc)[2][2][4][2], const Unit& u, int wr, int wc, int fr, int fq) const {
;     ...
;             const int row0 = u.pm * BM + wr * 64 + fr, col0 = colt + wc * 64 + 8 * fq;
; #pragma unroll
;             for (int ai = 0; ai < 2; ++ai)
; #pragma unroll
;                 for (int m = 0; m < 4; ++m) {
;                     const int row = row0 + ai * HALF + m * 16;
;                     float rstd = row_rstd(ss, row, fq); if (mode == 1) rstd *= 0.125f;
;                     bf16_t* rowp = base + (size_t)row * ldc + col0;
; #pragma unroll
;                     for (int bj = 0; bj < 2; ++bj) {
;                         f32x4 v0 = acc[ai][bj][m][0] * rstd, v1 = acc[ai][bj][m][1] * rstd;
.LBB0_196:
	v_lshl_add_u32 v2, s82, 8, v211
	v_lshlrev_b32_e32 v2, 7, v2
	v_mov_b32_e32 v3, 0
	v_lshl_add_u64 v[144:145], v[178:179], 0, v[2:3]
	v_add_u32_e32 v2, 0x1000, v2
	v_lshl_add_u64 v[208:209], v[178:179], 0, v[2:3]
	v_add_u32_e32 v2, 0x3000, v2
	v_lshl_add_u64 v[230:231], v[178:179], 0, v[2:3]
	v_add_u32_e32 v2, 0x1000, v2
	v_lshl_add_u64 v[238:239], v[178:179], 0, v[2:3]
	global_load_dwordx4 v[132:135], v[144:145], off
	global_load_dwordx4 v[136:139], v[144:145], off offset:16
	global_load_dwordx4 v[140:143], v[144:145], off offset:2048
	global_load_dwordx4 v[148:151], v[144:145], off offset:2064
	global_load_dwordx4 v[152:155], v[208:209], off
	global_load_dwordx4 v[184:187], v[208:209], off offset:16
	global_load_dwordx4 v[188:191], v[208:209], off offset:2048
	global_load_dwordx4 v[192:195], v[208:209], off offset:2064
	global_load_dwordx4 v[196:199], v[230:231], off
	global_load_dwordx4 v[200:203], v[230:231], off offset:16
	global_load_dwordx4 v[204:207], v[230:231], off offset:2048
	global_load_dwordx4 v[218:221], v[230:231], off offset:2064
	global_load_dwordx4 v[222:225], v[238:239], off
	global_load_dwordx4 v[226:229], v[238:239], off offset:16
	global_load_dwordx4 v[246:249], v[238:239], off offset:2048
	global_load_dwordx4 v[250:253], v[238:239], off offset:2064
	v_xor_b32_e32 v0, 16, v241
	v_xor_b32_e32 v162, 32, v241
	v_lshlrev_b32_e32 v0, 2, v0
	v_lshlrev_b32_e32 v162, 2, v162
	s_waitcnt vmcnt(14)
	v_pk_add_f32 v[132:133], v[132:133], v[134:135]
	v_pk_add_f32 v[136:137], v[136:137], v[138:139]
	v_pk_add_f32 v[132:133], v[132:133], v[136:137]
	v_add_f32_e32 v132, v132, v133
	s_waitcnt vmcnt(12)
	v_pk_add_f32 v[140:141], v[140:141], v[142:143]
	v_pk_add_f32 v[148:149], v[148:149], v[150:151]
	v_pk_add_f32 v[140:141], v[140:141], v[148:149]
	v_add_f32_e32 v140, v140, v141
	s_waitcnt vmcnt(10)
	v_pk_add_f32 v[152:153], v[152:153], v[154:155]
	v_pk_add_f32 v[184:185], v[184:185], v[186:187]
	v_pk_add_f32 v[152:153], v[152:153], v[184:185]
	v_add_f32_e32 v152, v152, v153
	s_waitcnt vmcnt(8)
	v_pk_add_f32 v[188:189], v[188:189], v[190:191]
	v_pk_add_f32 v[192:193], v[192:193], v[194:195]
	v_pk_add_f32 v[188:189], v[188:189], v[192:193]
	v_add_f32_e32 v188, v188, v189
	s_waitcnt vmcnt(6)
	v_pk_add_f32 v[196:197], v[196:197], v[198:199]
	v_pk_add_f32 v[200:201], v[200:201], v[202:203]
	v_pk_add_f32 v[196:197], v[196:197], v[200:201]
	v_add_f32_e32 v196, v196, v197
	s_waitcnt vmcnt(4)
	v_pk_add_f32 v[204:205], v[204:205], v[206:207]
	v_pk_add_f32 v[218:219], v[218:219], v[220:221]
	v_pk_add_f32 v[204:205], v[204:205], v[218:219]
	v_add_f32_e32 v204, v204, v205
	s_waitcnt vmcnt(2)
	v_pk_add_f32 v[222:223], v[222:223], v[224:225]
	v_pk_add_f32 v[226:227], v[226:227], v[228:229]
	v_pk_add_f32 v[222:223], v[222:223], v[226:227]
	v_add_f32_e32 v222, v222, v223
	s_waitcnt vmcnt(0)
	v_pk_add_f32 v[246:247], v[246:247], v[248:249]
	v_pk_add_f32 v[250:251], v[250:251], v[252:253]
	v_pk_add_f32 v[246:247], v[246:247], v[250:251]
	v_add_f32_e32 v246, v246, v247
	ds_bpermute_b32 v136, v0, v132
	ds_bpermute_b32 v148, v0, v140
	ds_bpermute_b32 v184, v0, v152
	ds_bpermute_b32 v192, v0, v188
	ds_bpermute_b32 v200, v0, v196
	ds_bpermute_b32 v218, v0, v204
	ds_bpermute_b32 v226, v0, v222
	ds_bpermute_b32 v250, v0, v246
	s_waitcnt lgkmcnt(0)
	v_add_f32_e32 v132, v132, v136
	v_add_f32_e32 v140, v140, v148
	v_add_f32_e32 v152, v152, v184
	v_add_f32_e32 v188, v188, v192
	v_add_f32_e32 v196, v196, v200
	v_add_f32_e32 v204, v204, v218
	v_add_f32_e32 v222, v222, v226
	v_add_f32_e32 v246, v246, v250
	ds_bpermute_b32 v136, v162, v132
	ds_bpermute_b32 v148, v162, v140
	ds_bpermute_b32 v184, v162, v152
	ds_bpermute_b32 v192, v162, v188
	ds_bpermute_b32 v200, v162, v196
	ds_bpermute_b32 v218, v162, v204
	ds_bpermute_b32 v226, v162, v222
	ds_bpermute_b32 v250, v162, v246
	s_waitcnt lgkmcnt(0)
	v_add_f32_e32 v132, v132, v136
	v_add_f32_e32 v140, v140, v148
	v_add_f32_e32 v152, v152, v184
	v_add_f32_e32 v188, v188, v192
	v_add_f32_e32 v196, v196, v200
	v_add_f32_e32 v204, v204, v218
	v_add_f32_e32 v222, v222, v226
	v_add_f32_e32 v246, v246, v250
	v_fmamk_f32 v132, v132, 0x3a000000, v243
	v_fmamk_f32 v140, v140, 0x3a000000, v243
	v_fmamk_f32 v152, v152, 0x3a000000, v243
	v_fmamk_f32 v188, v188, 0x3a000000, v243
	v_fmamk_f32 v196, v196, 0x3a000000, v243
	v_fmamk_f32 v204, v204, 0x3a000000, v243
	v_fmamk_f32 v222, v222, 0x3a000000, v243
	v_fmamk_f32 v246, v246, 0x3a000000, v243
	v_rsq_f32_e32 v132, v132
	v_rsq_f32_e32 v140, v140
	v_rsq_f32_e32 v152, v152
	v_rsq_f32_e32 v188, v188
	v_rsq_f32_e32 v196, v196
	v_rsq_f32_e32 v204, v204
	v_rsq_f32_e32 v222, v222
	v_rsq_f32_e32 v246, v246
	s_cmp_lg_u64 s[18:19], 0
	s_cselect_b32 s21, 0x3e000000, 1.0
	v_mul_f32_e32 v132, s21, v132
	v_mul_f32_e32 v140, s21, v140
	v_mul_f32_e32 v152, s21, v152
	v_mul_f32_e32 v188, s21, v188
	v_mul_f32_e32 v196, s21, v196
	v_mul_f32_e32 v204, s21, v204
	v_mul_f32_e32 v222, s21, v222
	v_mul_f32_e32 v246, s21, v246
	s_nop 0
	v_pk_mul_f32 v[128:129], v[128:129], v[132:133] op_sel_hi:[1,0]
	v_pk_mul_f32 v[130:131], v[130:131], v[132:133] op_sel_hi:[1,0]
	v_pk_mul_f32 v[124:125], v[124:125], v[132:133] op_sel_hi:[1,0]
	v_pk_mul_f32 v[126:127], v[126:127], v[132:133] op_sel_hi:[1,0]
	v_pk_mul_f32 v[120:121], v[120:121], v[132:133] op_sel_hi:[1,0]
	v_pk_mul_f32 v[122:123], v[122:123], v[132:133] op_sel_hi:[1,0]
	v_pk_mul_f32 v[116:117], v[116:117], v[132:133] op_sel_hi:[1,0]
	v_pk_mul_f32 v[118:119], v[118:119], v[132:133] op_sel_hi:[1,0]
	v_pk_mul_f32 v[112:113], v[112:113], v[140:141] op_sel_hi:[1,0]
	v_pk_mul_f32 v[114:115], v[114:115], v[140:141] op_sel_hi:[1,0]
; __device__ __forceinline__ f32x4 gelu4(f32x4 v) { return (f32x4){gelu_tanh(v[0]), gelu_tanh(v[1]), gelu_tanh(v[2]), gelu_tanh(v[3])}; }
; __device__ __forceinline__ f32x4 sigm4(f32x4 v) { return (f32x4){sigmoid_f(v[0]), sigmoid_f(v[1]), sigmoid_f(v[2]), sigmoid_f(v[3])}; }
; __device__ __forceinline__ u32x4 pack8(f32x4 a, f32x4 b) { u32x4 w; w.x = cvt_pk_bf16(a[0], a[1]); w.y = cvt_pk_bf16(a[2], a[3]); w.z = cvt_pk_bf16(b[0], b[1]); w.w = cvt_pk_bf16(b[2], b[3]); return w; }
;     __device__ __forceinline__ void operator()(f32x4 (&acc)[2][2][4][2], const Unit& u, int wr, int wc, int fr, int fq) const {
;     ...
;             const int row0 = u.pm * BM + wr * 64 + fr, col0 = colt + wc * 64 + 8 * fq;
; #pragma unroll
;             for (int ai = 0; ai < 2; ++ai)
; #pragma unroll
;                 for (int m = 0; m < 4; ++m) {
;                     const int row = row0 + ai * HALF + m * 16;
;                     float rstd = row_rstd(ss, row, fq); if (mode == 1) rstd *= 0.125f;
;                     bf16_t* rowp = base + (size_t)row * ldc + col0;
; #pragma unroll
;                     for (int bj = 0; bj < 2; ++bj) {
;                         f32x4 v0 = acc[ai][bj][m][0] * rstd, v1 = acc[ai][bj][m][1] * rstd;
;                         if (mode == 3) { u32x2 w; w.x = gate_q4(sigm4(v0)); w.y = gate_q4(sigm4(v1)); *(u32x2*)((unsigned char*)Gt + (size_t)row * 4096 + col0 + bj * 32) = w; continue; }
;                         if (mode == 0) { v0 = gelu4(v0); v1 = gelu4(v1); }
;                         *(u32x4*)(rowp + bj * 32) = pack8(v0, v1);
	v_pk_mul_f32 v[108:109], v[108:109], v[140:141] op_sel_hi:[1,0]
	v_pk_mul_f32 v[110:111], v[110:111], v[140:141] op_sel_hi:[1,0]
	v_pk_mul_f32 v[104:105], v[104:105], v[140:141] op_sel_hi:[1,0]
	v_pk_mul_f32 v[106:107], v[106:107], v[140:141] op_sel_hi:[1,0]
	v_pk_mul_f32 v[100:101], v[100:101], v[140:141] op_sel_hi:[1,0]
	v_pk_mul_f32 v[102:103], v[102:103], v[140:141] op_sel_hi:[1,0]
	v_pk_mul_f32 v[96:97], v[96:97], v[152:153] op_sel_hi:[1,0]
	v_pk_mul_f32 v[98:99], v[98:99], v[152:153] op_sel_hi:[1,0]
	v_pk_mul_f32 v[92:93], v[92:93], v[152:153] op_sel_hi:[1,0]
	v_pk_mul_f32 v[94:95], v[94:95], v[152:153] op_sel_hi:[1,0]
	v_pk_mul_f32 v[88:89], v[88:89], v[152:153] op_sel_hi:[1,0]
	v_pk_mul_f32 v[90:91], v[90:91], v[152:153] op_sel_hi:[1,0]
	v_pk_mul_f32 v[84:85], v[84:85], v[152:153] op_sel_hi:[1,0]
	v_pk_mul_f32 v[86:87], v[86:87], v[152:153] op_sel_hi:[1,0]
	v_pk_mul_f32 v[80:81], v[80:81], v[188:189] op_sel_hi:[1,0]
	v_pk_mul_f32 v[82:83], v[82:83], v[188:189] op_sel_hi:[1,0]
	v_pk_mul_f32 v[76:77], v[76:77], v[188:189] op_sel_hi:[1,0]
	v_pk_mul_f32 v[78:79], v[78:79], v[188:189] op_sel_hi:[1,0]
	v_pk_mul_f32 v[72:73], v[72:73], v[188:189] op_sel_hi:[1,0]
	v_pk_mul_f32 v[74:75], v[74:75], v[188:189] op_sel_hi:[1,0]
	v_pk_mul_f32 v[68:69], v[68:69], v[188:189] op_sel_hi:[1,0]
	v_pk_mul_f32 v[70:71], v[70:71], v[188:189] op_sel_hi:[1,0]
	v_pk_mul_f32 v[64:65], v[64:65], v[196:197] op_sel_hi:[1,0]
	v_pk_mul_f32 v[66:67], v[66:67], v[196:197] op_sel_hi:[1,0]
	v_pk_mul_f32 v[60:61], v[60:61], v[196:197] op_sel_hi:[1,0]
	v_pk_mul_f32 v[62:63], v[62:63], v[196:197] op_sel_hi:[1,0]
	v_pk_mul_f32 v[56:57], v[56:57], v[196:197] op_sel_hi:[1,0]
	v_pk_mul_f32 v[58:59], v[58:59], v[196:197] op_sel_hi:[1,0]
	v_pk_mul_f32 v[52:53], v[52:53], v[196:197] op_sel_hi:[1,0]
	v_pk_mul_f32 v[54:55], v[54:55], v[196:197] op_sel_hi:[1,0]
	v_pk_mul_f32 v[48:49], v[48:49], v[204:205] op_sel_hi:[1,0]
	v_pk_mul_f32 v[50:51], v[50:51], v[204:205] op_sel_hi:[1,0]
	v_pk_mul_f32 v[44:45], v[44:45], v[204:205] op_sel_hi:[1,0]
	v_pk_mul_f32 v[46:47], v[46:47], v[204:205] op_sel_hi:[1,0]
	v_pk_mul_f32 v[40:41], v[40:41], v[204:205] op_sel_hi:[1,0]
	v_pk_mul_f32 v[42:43], v[42:43], v[204:205] op_sel_hi:[1,0]
	v_pk_mul_f32 v[36:37], v[36:37], v[204:205] op_sel_hi:[1,0]
	v_pk_mul_f32 v[38:39], v[38:39], v[204:205] op_sel_hi:[1,0]
	v_pk_mul_f32 v[32:33], v[32:33], v[222:223] op_sel_hi:[1,0]
	v_pk_mul_f32 v[34:35], v[34:35], v[222:223] op_sel_hi:[1,0]
	v_pk_mul_f32 v[28:29], v[28:29], v[222:223] op_sel_hi:[1,0]
	v_pk_mul_f32 v[30:31], v[30:31], v[222:223] op_sel_hi:[1,0]
	v_pk_mul_f32 v[24:25], v[24:25], v[222:223] op_sel_hi:[1,0]
	v_pk_mul_f32 v[26:27], v[26:27], v[222:223] op_sel_hi:[1,0]
	v_pk_mul_f32 v[20:21], v[20:21], v[222:223] op_sel_hi:[1,0]
	v_pk_mul_f32 v[22:23], v[22:23], v[222:223] op_sel_hi:[1,0]
	v_pk_mul_f32 v[16:17], v[16:17], v[246:247] op_sel_hi:[1,0]
	v_pk_mul_f32 v[18:19], v[18:19], v[246:247] op_sel_hi:[1,0]
	v_pk_mul_f32 v[12:13], v[12:13], v[246:247] op_sel_hi:[1,0]
	v_pk_mul_f32 v[14:15], v[14:15], v[246:247] op_sel_hi:[1,0]
	v_pk_mul_f32 v[8:9], v[8:9], v[246:247] op_sel_hi:[1,0]
	v_pk_mul_f32 v[10:11], v[10:11], v[246:247] op_sel_hi:[1,0]
	v_pk_mul_f32 v[4:5], v[4:5], v[246:247] op_sel_hi:[1,0]
	v_pk_mul_f32 v[6:7], v[6:7], v[246:247] op_sel_hi:[1,0]
	v_lshl_add_u32 v184, s82, 8, v211
	v_add_u32_e32 v185, s20, v215
	s_mov_b32 s42, 1.0
	s_mov_b32 s43, 1.0
	s_and_b64 vcc, exec, s[12:13]
	s_cbranch_vccnz .Lp1e_gates
	v_lshlrev_b32_e32 v186, 11, v184
	v_lshl_add_u32 v186, v185, 1, v186
	s_and_b64 vcc, exec, s[16:17]
	s_cbranch_vccnz .Lp1e_gelu
	v_cvt_pk_bf16_f32 v206, v128, v129
	v_cvt_pk_bf16_f32 v207, v130, v131
	v_cvt_pk_bf16_f32 v208, v124, v125
	v_cvt_pk_bf16_f32 v209, v126, v127
	global_store_dwordx4 v186, v[206:209], s[34:35]
	v_cvt_pk_bf16_f32 v218, v120, v121
	v_cvt_pk_bf16_f32 v219, v122, v123
	v_cvt_pk_bf16_f32 v220, v116, v117
	v_cvt_pk_bf16_f32 v221, v118, v119
	global_store_dwordx4 v186, v[218:221], s[34:35] offset:64
	v_add_u32_e32 v187, 0x8000, v186
	v_cvt_pk_bf16_f32 v224, v112, v113
	v_cvt_pk_bf16_f32 v225, v114, v115
	v_cvt_pk_bf16_f32 v226, v108, v109
	v_cvt_pk_bf16_f32 v227, v110, v111
	global_store_dwordx4 v187, v[224:227], s[34:35]
	v_cvt_pk_bf16_f32 v228, v104, v105
	v_cvt_pk_bf16_f32 v229, v106, v107
	v_cvt_pk_bf16_f32 v230, v100, v101
	v_cvt_pk_bf16_f32 v231, v102, v103
	global_store_dwordx4 v187, v[228:231], s[34:35] offset:64
	v_add_u32_e32 v187, 0x10000, v186
	v_cvt_pk_bf16_f32 v206, v96, v97
	v_cvt_pk_bf16_f32 v207, v98, v99
	v_cvt_pk_bf16_f32 v208, v92, v93
	v_cvt_pk_bf16_f32 v209, v94, v95
	global_store_dwordx4 v187, v[206:209], s[34:35]
	v_cvt_pk_bf16_f32 v218, v88, v89
	v_cvt_pk_bf16_f32 v219, v90, v91
	v_cvt_pk_bf16_f32 v220, v84, v85
	v_cvt_pk_bf16_f32 v221, v86, v87
	global_store_dwordx4 v187, v[218:221], s[34:35] offset:64
	v_add_u32_e32 v187, 0x18000, v186
	v_cvt_pk_bf16_f32 v224, v80, v81
	v_cvt_pk_bf16_f32 v225, v82, v83
	v_cvt_pk_bf16_f32 v226, v76, v77
	v_cvt_pk_bf16_f32 v227, v78, v79
	global_store_dwordx4 v187, v[224:227], s[34:35]
	v_cvt_pk_bf16_f32 v228, v72, v73
	v_cvt_pk_bf16_f32 v229, v74, v75
	v_cvt_pk_bf16_f32 v230, v68, v69
	v_cvt_pk_bf16_f32 v231, v70, v71
	global_store_dwordx4 v187, v[228:231], s[34:35] offset:64
	v_add_u32_e32 v187, 0x40000, v186
	v_cvt_pk_bf16_f32 v206, v64, v65
	v_cvt_pk_bf16_f32 v207, v66, v67
	v_cvt_pk_bf16_f32 v208, v60, v61
	v_cvt_pk_bf16_f32 v209, v62, v63
	global_store_dwordx4 v187, v[206:209], s[34:35]
	v_cvt_pk_bf16_f32 v218, v56, v57
	v_cvt_pk_bf16_f32 v219, v58, v59
	v_cvt_pk_bf16_f32 v220, v52, v53
	v_cvt_pk_bf16_f32 v221, v54, v55
	global_store_dwordx4 v187, v[218:221], s[34:35] offset:64
	v_add_u32_e32 v187, 0x48000, v186
	v_cvt_pk_bf16_f32 v224, v48, v49
	v_cvt_pk_bf16_f32 v225, v50, v51
	v_cvt_pk_bf16_f32 v226, v44, v45
	v_cvt_pk_bf16_f32 v227, v46, v47
	global_store_dwordx4 v187, v[224:227], s[34:35]
	v_cvt_pk_bf16_f32 v228, v40, v41
	v_cvt_pk_bf16_f32 v229, v42, v43
	v_cvt_pk_bf16_f32 v230, v36, v37
	v_cvt_pk_bf16_f32 v231, v38, v39
	global_store_dwordx4 v187, v[228:231], s[34:35] offset:64
	v_add_u32_e32 v187, 0x50000, v186
	v_cvt_pk_bf16_f32 v206, v32, v33
	v_cvt_pk_bf16_f32 v207, v34, v35
	v_cvt_pk_bf16_f32 v208, v28, v29
	v_cvt_pk_bf16_f32 v209, v30, v31
	global_store_dwordx4 v187, v[206:209], s[34:35]
	v_cvt_pk_bf16_f32 v218, v24, v25
	v_cvt_pk_bf16_f32 v219, v26, v27
	v_cvt_pk_bf16_f32 v220, v20, v21
	v_cvt_pk_bf16_f32 v221, v22, v23
	global_store_dwordx4 v187, v[218:221], s[34:35] offset:64
	v_add_u32_e32 v187, 0x58000, v186
	v_cvt_pk_bf16_f32 v224, v16, v17
	v_cvt_pk_bf16_f32 v225, v18, v19
	v_cvt_pk_bf16_f32 v226, v12, v13
	v_cvt_pk_bf16_f32 v227, v14, v15
	global_store_dwordx4 v187, v[224:227], s[34:35]
	v_cvt_pk_bf16_f32 v228, v8, v9
	v_cvt_pk_bf16_f32 v229, v10, v11
	v_cvt_pk_bf16_f32 v230, v4, v5
	v_cvt_pk_bf16_f32 v231, v6, v7
	global_store_dwordx4 v187, v[228:231], s[34:35] offset:64
	s_branch .Lp1e_done

; __device__ __forceinline__ float row_rstd(const float* ssp, int row, int fq) {
;     const f32x4 a = *(const f32x4*)(ssp + (size_t)row * 32 + 8 * fq), b = *(const f32x4*)(ssp + (size_t)row * 32 + 8 * fq + 4);
;     float s = ((a[0] + a[1]) + (a[2] + a[3])) + ((b[0] + b[1]) + (b[2] + b[3]));
;     s += __shfl_xor(s, 16); s += __shfl_xor(s, 32);
;     return __builtin_amdgcn_rsqf(s * (1.0f / 2048.0f) + 1e-6f);
;     __device__ __forceinline__ void operator()(f32x4 (&acc)[2][2][4][2], const Unit& u, int wr, int wc, int fr, int fq) const {
;         const int row0 = u.pm * BM + wr * 64 + fr;
; #pragma unroll
;         for (int ai = 0; ai < 2; ++ai)
; #pragma unroll
;             for (int m = 0; m < 4; ++m) { const float rstd = row_rstd(ss, row0 + ai * HALF + m * 16, fq);
; #pragma unroll
;                 for (int bj = 0; bj < 2; ++bj) { acc[ai][bj][m][0] *= rstd; acc[ai][bj][m][1] *= rstd; } }
; #pragma unroll
;         for (int n = 0; n < 2; ++n) {
;             const int j4 = u.pn * 128 + wc * 32 + 8 * fq + 4 * n;
;             f32x4 kc[2][3], bc[2];
; #pragma unroll
;             for (int bj = 0; bj < 2; ++bj) { bc[bj] = *(const f32x4*)(cb + bj * FF + j4);
; #pragma unroll
;                 for (int w = 0; w < 3; ++w) kc[bj][w] = *(const f32x4*)(ck + w * NUP + bj * FF + j4); }
.LBB0_755:
	s_waitcnt vmcnt(14)
	v_pk_add_f32 v[174:175], v[174:175], v[176:177]
	v_pk_add_f32 v[178:179], v[178:179], v[180:181]
	v_pk_add_f32 v[174:175], v[174:175], v[178:179]
	v_add_f32_e32 v130, v174, v175
	s_waitcnt vmcnt(12)
	v_pk_add_f32 v[182:183], v[182:183], v[184:185]
	v_pk_add_f32 v[186:187], v[186:187], v[188:189]
	v_pk_add_f32 v[182:183], v[182:183], v[186:187]
	v_add_f32_e32 v132, v182, v183
	s_waitcnt vmcnt(10)
	v_pk_add_f32 v[190:191], v[190:191], v[192:193]
	v_pk_add_f32 v[194:195], v[194:195], v[196:197]
	v_pk_add_f32 v[190:191], v[190:191], v[194:195]
	v_add_f32_e32 v134, v190, v191
	s_waitcnt vmcnt(8)
	v_pk_add_f32 v[198:199], v[198:199], v[200:201]
	v_pk_add_f32 v[202:203], v[202:203], v[204:205]
	v_pk_add_f32 v[198:199], v[198:199], v[202:203]
	v_add_f32_e32 v136, v198, v199
	s_waitcnt vmcnt(6)
	v_pk_add_f32 v[206:207], v[206:207], v[208:209]
	v_pk_add_f32 v[210:211], v[210:211], v[212:213]
	v_pk_add_f32 v[206:207], v[206:207], v[210:211]
	v_add_f32_e32 v138, v206, v207
	s_waitcnt vmcnt(4)
	v_pk_add_f32 v[214:215], v[214:215], v[216:217]
	v_pk_add_f32 v[218:219], v[218:219], v[220:221]
	v_pk_add_f32 v[214:215], v[214:215], v[218:219]
	v_add_f32_e32 v140, v214, v215
	s_waitcnt vmcnt(2)
	v_pk_add_f32 v[222:223], v[222:223], v[224:225]
	v_pk_add_f32 v[226:227], v[226:227], v[228:229]
	v_pk_add_f32 v[222:223], v[222:223], v[226:227]
	v_add_f32_e32 v142, v222, v223
	s_waitcnt vmcnt(0)
	v_pk_add_f32 v[230:231], v[230:231], v[232:233]
	v_pk_add_f32 v[234:235], v[234:235], v[236:237]
	v_pk_add_f32 v[230:231], v[230:231], v[234:235]
	v_add_f32_e32 v144, v230, v231
	v_lshl_or_b32 v242, s16, 7, v250
	v_lshlrev_b32_e32 v252, 1, v242
	v_lshlrev_b32_e32 v242, 2, v242
	v_add_u32_e32 v131, 0x5600, v242
	v_add_u32_e32 v133, 0xac00, v242
	v_add_u32_e32 v135, 0x10200, v242
	v_add_u32_e32 v137, 0x15800, v242
	v_add_u32_e32 v139, 0x1ae00, v242
	global_load_dwordx4 v[182:185], v242, s[18:19]
	global_load_dwordx4 v[186:189], v133, s[18:19]
	global_load_dwordx4 v[190:193], v137, s[18:19]
	global_load_dwordx4 v[194:197], v242, s[20:21]
	global_load_dwordx4 v[198:201], v131, s[18:19]
	global_load_dwordx4 v[202:205], v135, s[18:19]
	global_load_dwordx4 v[206:209], v139, s[18:19]
	global_load_dwordx4 v[210:213], v131, s[20:21]
	ds_bpermute_b32 v174, v238, v130
	ds_bpermute_b32 v175, v238, v132
	ds_bpermute_b32 v176, v238, v134
	ds_bpermute_b32 v177, v238, v136
	ds_bpermute_b32 v178, v238, v138
	ds_bpermute_b32 v179, v238, v140
	ds_bpermute_b32 v180, v238, v142
	ds_bpermute_b32 v181, v238, v144
	s_waitcnt lgkmcnt(0)
	v_add_f32_e32 v130, v130, v174
	v_add_f32_e32 v132, v132, v175
	v_add_f32_e32 v134, v134, v176
	v_add_f32_e32 v136, v136, v177
	v_add_f32_e32 v138, v138, v178
	v_add_f32_e32 v140, v140, v179
	v_add_f32_e32 v142, v142, v180
	v_add_f32_e32 v144, v144, v181
	ds_bpermute_b32 v174, v239, v130
	ds_bpermute_b32 v175, v239, v132
	ds_bpermute_b32 v176, v239, v134
	ds_bpermute_b32 v177, v239, v136
	ds_bpermute_b32 v178, v239, v138
	ds_bpermute_b32 v179, v239, v140
	ds_bpermute_b32 v180, v239, v142
	ds_bpermute_b32 v181, v239, v144
	s_waitcnt lgkmcnt(0)
	v_add_f32_e32 v130, v130, v174
	v_add_f32_e32 v132, v132, v175
	v_add_f32_e32 v134, v134, v176
	v_add_f32_e32 v136, v136, v177
	v_add_f32_e32 v138, v138, v178
	v_add_f32_e32 v140, v140, v179
	v_add_f32_e32 v142, v142, v180
	v_add_f32_e32 v144, v144, v181
	v_fmamk_f32 v130, v130, 0x3a000000, v243
	v_fmamk_f32 v132, v132, 0x3a000000, v243
	v_fmamk_f32 v134, v134, 0x3a000000, v243
	v_fmamk_f32 v136, v136, 0x3a000000, v243
	v_fmamk_f32 v138, v138, 0x3a000000, v243
	v_fmamk_f32 v140, v140, 0x3a000000, v243
	v_fmamk_f32 v142, v142, 0x3a000000, v243
	v_fmamk_f32 v144, v144, 0x3a000000, v243
	v_rsq_f32_e32 v130, v130
	v_rsq_f32_e32 v132, v132
	v_rsq_f32_e32 v134, v134
	v_rsq_f32_e32 v136, v136
	v_rsq_f32_e32 v138, v138
	v_rsq_f32_e32 v140, v140
	v_rsq_f32_e32 v142, v142
	v_rsq_f32_e32 v144, v144
	s_nop 0
	v_pk_mul_f32 v[126:127], v[126:127], v[130:131] op_sel_hi:[1,0]
	v_pk_mul_f32 v[128:129], v[128:129], v[130:131] op_sel_hi:[1,0]
	v_pk_mul_f32 v[62:63], v[62:63], v[130:131] op_sel_hi:[1,0]
	v_pk_mul_f32 v[64:65], v[64:65], v[130:131] op_sel_hi:[1,0]
	v_pk_mul_f32 v[122:123], v[122:123], v[130:131] op_sel_hi:[1,0]
	v_pk_mul_f32 v[124:125], v[124:125], v[130:131] op_sel_hi:[1,0]
	v_pk_mul_f32 v[54:55], v[54:55], v[130:131] op_sel_hi:[1,0]
	v_pk_mul_f32 v[56:57], v[56:57], v[130:131] op_sel_hi:[1,0]
	v_pk_mul_f32 v[118:119], v[118:119], v[132:133] op_sel_hi:[1,0]
	v_pk_mul_f32 v[120:121], v[120:121], v[132:133] op_sel_hi:[1,0]
	v_pk_mul_f32 v[58:59], v[58:59], v[132:133] op_sel_hi:[1,0]
	v_pk_mul_f32 v[60:61], v[60:61], v[132:133] op_sel_hi:[1,0]
	v_pk_mul_f32 v[114:115], v[114:115], v[132:133] op_sel_hi:[1,0]
	v_pk_mul_f32 v[116:117], v[116:117], v[132:133] op_sel_hi:[1,0]
	v_pk_mul_f32 v[50:51], v[50:51], v[132:133] op_sel_hi:[1,0]
	v_pk_mul_f32 v[52:53], v[52:53], v[132:133] op_sel_hi:[1,0]
	v_pk_mul_f32 v[110:111], v[110:111], v[134:135] op_sel_hi:[1,0]
	v_pk_mul_f32 v[112:113], v[112:113], v[134:135] op_sel_hi:[1,0]
	v_pk_mul_f32 v[46:47], v[46:47], v[134:135] op_sel_hi:[1,0]
	v_pk_mul_f32 v[48:49], v[48:49], v[134:135] op_sel_hi:[1,0]
	v_pk_mul_f32 v[102:103], v[102:103], v[134:135] op_sel_hi:[1,0]
	v_pk_mul_f32 v[104:105], v[104:105], v[134:135] op_sel_hi:[1,0]
	v_pk_mul_f32 v[38:39], v[38:39], v[134:135] op_sel_hi:[1,0]
	v_pk_mul_f32 v[40:41], v[40:41], v[134:135] op_sel_hi:[1,0]
	v_pk_mul_f32 v[106:107], v[106:107], v[136:137] op_sel_hi:[1,0]
	v_pk_mul_f32 v[108:109], v[108:109], v[136:137] op_sel_hi:[1,0]
	v_pk_mul_f32 v[42:43], v[42:43], v[136:137] op_sel_hi:[1,0]
;     __device__ __forceinline__ void operator()(f32x4 (&acc)[2][2][4][2], const Unit& u, int wr, int wc, int fr, int fq) const {
;     ...
;             for (int m = 0; m < 4; ++m) { const float rstd = row_rstd(ss, row0 + ai * HALF + m * 16, fq);
; #pragma unroll
;                 for (int bj = 0; bj < 2; ++bj) { acc[ai][bj][m][0] *= rstd; acc[ai][bj][m][1] *= rstd; } }
; #pragma unroll
;         for (int n = 0; n < 2; ++n) {
;             const int j4 = u.pn * 128 + wc * 32 + 8 * fq + 4 * n;
;             f32x4 kc[2][3], bc[2];
; #pragma unroll
;             for (int bj = 0; bj < 2; ++bj) { bc[bj] = *(const f32x4*)(cb + bj * FF + j4);
; #pragma unroll
;                 for (int w = 0; w < 3; ++w) kc[bj][w] = *(const f32x4*)(ck + w * NUP + bj * FF + j4); }
; #pragma unroll
;             for (int ai = 0; ai < 2; ++ai) {
;                 const int grp = u.pm * 4 + ai * 2 + wr;
; #pragma unroll
;                 for (int m = 0; m < 4; ++m) {
;                     f32x4 cv[2];
; #pragma unroll
;                     for (int bj = 0; bj < 2; ++bj) {
;                         const f32x4 cur = acc[ai][bj][m][n], lo = acc[ai][bj][m > 0 ? m - 1 : 0][n], hi = acc[ai][bj][m < 3 ? m + 1 : 3][n];
;                         f32x4 pv, nv;
; #pragma unroll
;                         for (int idx = 0; idx < 4; ++idx) {
;                             const float y = (fr == 15) ? lo[idx] : cur[idx], z = (fr == 0) ? hi[idx] : cur[idx];
;                             pv[idx] = __int_as_float(__builtin_amdgcn_update_dpp(0, __float_as_int(y), 0x121, 0xf, 0xf, false));
;                             nv[idx] = __int_as_float(__builtin_amdgcn_update_dpp(0, __float_as_int(z), 0x12f, 0xf, 0xf, false));
;                         }
;                         cv[bj] = kc[bj][0] * pv + kc[bj][1] * cur + kc[bj][2] * nv + bc[bj];
;                     }
;                     const int row = row0 + ai * HALF + m * 16;
;                     const bool edge = (m == 0 && fr == 0) || (m == 3 && fr == 15);
;                     if (!edge) { const f32x4 gt = cv[0], vl = cv[1];
;                         u32x2 w; w.x = cvt_pk_bf16(gt[0] * sigmoid_f(gt[0]) * vl[0], gt[1] * sigmoid_f(gt[1]) * vl[1]); w.y = cvt_pk_bf16(gt[2] * sigmoid_f(gt[2]) * vl[2], gt[3] * sigmoid_f(gt[3]) * vl[3]);
;                         *(u32x2*)(ACT + (size_t)row * FF + j4) = w; }
;                     if (m == 0 && fr < 2) {
	v_pk_mul_f32 v[44:45], v[44:45], v[136:137] op_sel_hi:[1,0]
	v_pk_mul_f32 v[98:99], v[98:99], v[136:137] op_sel_hi:[1,0]
	v_pk_mul_f32 v[100:101], v[100:101], v[136:137] op_sel_hi:[1,0]
	v_pk_mul_f32 v[34:35], v[34:35], v[136:137] op_sel_hi:[1,0]
	v_pk_mul_f32 v[36:37], v[36:37], v[136:137] op_sel_hi:[1,0]
	v_pk_mul_f32 v[94:95], v[94:95], v[138:139] op_sel_hi:[1,0]
	v_pk_mul_f32 v[96:97], v[96:97], v[138:139] op_sel_hi:[1,0]
	v_pk_mul_f32 v[30:31], v[30:31], v[138:139] op_sel_hi:[1,0]
	v_pk_mul_f32 v[32:33], v[32:33], v[138:139] op_sel_hi:[1,0]
	v_pk_mul_f32 v[86:87], v[86:87], v[138:139] op_sel_hi:[1,0]
	v_pk_mul_f32 v[88:89], v[88:89], v[138:139] op_sel_hi:[1,0]
	v_pk_mul_f32 v[22:23], v[22:23], v[138:139] op_sel_hi:[1,0]
	v_pk_mul_f32 v[24:25], v[24:25], v[138:139] op_sel_hi:[1,0]
	v_pk_mul_f32 v[90:91], v[90:91], v[140:141] op_sel_hi:[1,0]
	v_pk_mul_f32 v[92:93], v[92:93], v[140:141] op_sel_hi:[1,0]
	v_pk_mul_f32 v[26:27], v[26:27], v[140:141] op_sel_hi:[1,0]
	v_pk_mul_f32 v[28:29], v[28:29], v[140:141] op_sel_hi:[1,0]
	v_pk_mul_f32 v[82:83], v[82:83], v[140:141] op_sel_hi:[1,0]
	v_pk_mul_f32 v[84:85], v[84:85], v[140:141] op_sel_hi:[1,0]
	v_pk_mul_f32 v[18:19], v[18:19], v[140:141] op_sel_hi:[1,0]
	v_pk_mul_f32 v[20:21], v[20:21], v[140:141] op_sel_hi:[1,0]
	v_pk_mul_f32 v[78:79], v[78:79], v[142:143] op_sel_hi:[1,0]
	v_pk_mul_f32 v[80:81], v[80:81], v[142:143] op_sel_hi:[1,0]
	v_pk_mul_f32 v[14:15], v[14:15], v[142:143] op_sel_hi:[1,0]
	v_pk_mul_f32 v[16:17], v[16:17], v[142:143] op_sel_hi:[1,0]
	v_pk_mul_f32 v[70:71], v[70:71], v[142:143] op_sel_hi:[1,0]
	v_pk_mul_f32 v[72:73], v[72:73], v[142:143] op_sel_hi:[1,0]
	v_pk_mul_f32 v[6:7], v[6:7], v[142:143] op_sel_hi:[1,0]
	v_pk_mul_f32 v[8:9], v[8:9], v[142:143] op_sel_hi:[1,0]
	v_pk_mul_f32 v[74:75], v[74:75], v[144:145] op_sel_hi:[1,0]
	v_pk_mul_f32 v[76:77], v[76:77], v[144:145] op_sel_hi:[1,0]
	v_pk_mul_f32 v[10:11], v[10:11], v[144:145] op_sel_hi:[1,0]
	v_pk_mul_f32 v[12:13], v[12:13], v[144:145] op_sel_hi:[1,0]
	v_pk_mul_f32 v[66:67], v[66:67], v[144:145] op_sel_hi:[1,0]
	v_pk_mul_f32 v[68:69], v[68:69], v[144:145] op_sel_hi:[1,0]
	v_pk_mul_f32 v[2:3], v[2:3], v[144:145] op_sel_hi:[1,0]
	v_pk_mul_f32 v[4:5], v[4:5], v[144:145] op_sel_hi:[1,0]
	s_mov_b32 s34, 0xbfb8aa3b
	s_mov_b32 s35, 0xbfb8aa3b
	s_mov_b32 s36, 1.0
	s_mov_b32 s37, 1.0
	v_lshl_add_u32 v238, s12, 8, v247
	v_mul_u32_u24_e32 v238, 0x2b00, v238
	v_add_u32_e32 v238, v238, v252
	s_lshl_b32 s13, s12, 4
	s_add_i32 s13, s13, s92
	v_add_u32_e32 v253, s13, v246
	v_mul_u32_u24_e32 v253, 0x5600, v253
	v_add_u32_e32 v253, v253, v252
	v_add_u32_e32 v239, 0x2b00, v253
	v_cvt_pk_bf16_f32 v230, v126, v127
	v_cvt_pk_bf16_f32 v231, v128, v129
	v_cvt_pk_bf16_f32 v232, v62, v63
	v_cvt_pk_bf16_f32 v233, v64, v65
	s_and_saveexec_b64 s[16:17], s[46:47]
	global_store_dwordx4 v253, v[230:233], s[54:55]
	s_or_b64 exec, exec, s[16:17]
	v_cvt_pk_bf16_f32 v234, v122, v123
	v_cvt_pk_bf16_f32 v235, v124, v125
	v_cvt_pk_bf16_f32 v236, v54, v55
	v_cvt_pk_bf16_f32 v237, v56, v57
	s_and_saveexec_b64 s[16:17], s[46:47]
	global_store_dwordx4 v239, v[234:237], s[54:55]
	s_or_b64 exec, exec, s[16:17]
	v_add_u32_e32 v253, s13, v246
	v_add_u32_e32 v253, 8, v253
	v_mul_u32_u24_e32 v253, 0x5600, v253
	v_add_u32_e32 v253, v253, v252
	v_add_u32_e32 v239, 0x2b00, v253
	v_cvt_pk_bf16_f32 v214, v94, v95
	v_cvt_pk_bf16_f32 v215, v96, v97
	v_cvt_pk_bf16_f32 v216, v30, v31
	v_cvt_pk_bf16_f32 v217, v32, v33
	s_and_saveexec_b64 s[16:17], s[46:47]
	global_store_dwordx4 v253, v[214:217], s[54:55]
	s_or_b64 exec, exec, s[16:17]
	v_cvt_pk_bf16_f32 v218, v86, v87
	v_cvt_pk_bf16_f32 v219, v88, v89
	v_cvt_pk_bf16_f32 v220, v22, v23
	v_cvt_pk_bf16_f32 v221, v24, v25
	s_and_saveexec_b64 s[16:17], s[46:47]
	global_store_dwordx4 v239, v[218:221], s[54:55]
	s_or_b64 exec, exec, s[16:17]
	v_add_u32_e32 v253, s13, v249
	v_mul_u32_u24_e32 v253, 0x5600, v253
	v_add_u32_e32 v253, v253, v252
	v_add_u32_e32 v239, 0x2b00, v253
	v_cvt_pk_bf16_f32 v230, v106, v107
	v_cvt_pk_bf16_f32 v231, v108, v109
	v_cvt_pk_bf16_f32 v232, v42, v43
	v_cvt_pk_bf16_f32 v233, v44, v45
	s_and_saveexec_b64 s[16:17], s[48:49]
	global_store_dwordx4 v253, v[230:233], s[54:55]
	s_or_b64 exec, exec, s[16:17]
	v_cvt_pk_bf16_f32 v234, v98, v99
	v_cvt_pk_bf16_f32 v235, v100, v101
	v_cvt_pk_bf16_f32 v236, v34, v35
	v_cvt_pk_bf16_f32 v237, v36, v37
	s_and_saveexec_b64 s[16:17], s[48:49]
	global_store_dwordx4 v239, v[234:237], s[54:55]
	s_or_b64 exec, exec, s[16:17]
	v_add_u32_e32 v253, s13, v249
	v_add_u32_e32 v253, 8, v253
	v_mul_u32_u24_e32 v253, 0x5600, v253
	v_add_u32_e32 v253, v253, v252
	v_add_u32_e32 v239, 0x2b00, v253
	v_cvt_pk_bf16_f32 v214, v74, v75
	v_cvt_pk_bf16_f32 v215, v76, v77
	v_cvt_pk_bf16_f32 v216, v10, v11
	v_cvt_pk_bf16_f32 v217, v12, v13
	s_and_saveexec_b64 s[16:17], s[48:49]
	global_store_dwordx4 v253, v[214:217], s[54:55]
	s_or_b64 exec, exec, s[16:17]
	v_cvt_pk_bf16_f32 v218, v66, v67
	v_cvt_pk_bf16_f32 v219, v68, v69
	v_cvt_pk_bf16_f32 v220, v2, v3
	v_cvt_pk_bf16_f32 v221, v4, v5
	s_and_saveexec_b64 s[16:17], s[48:49]
	global_store_dwordx4 v239, v[218:221], s[54:55]
	s_or_b64 exec, exec, s[16:17]
	s_waitcnt vmcnt(8)
; __device__ __forceinline__ unsigned cvt_pk_bf16(float lo, float hi) { unsigned r; asm volatile("v_cvt_pk_bf16_f32 %0, %1, %2" : "=v"(r) : "v"(lo), "v"(hi)); return r; }
; __device__ __forceinline__ float fast_rcp(float x) { return __builtin_amdgcn_rcpf(x); }
; __device__ __forceinline__ float fast_exp2(float x) { return __builtin_amdgcn_exp2f(x); }
; __device__ __forceinline__ float sigmoid_f(float x) { return fast_rcp(1.0f + fast_exp2(-1.4426950409f * x)); }
;     __device__ __forceinline__ void operator()(f32x4 (&acc)[2][2][4][2], const Unit& u, int wr, int wc, int fr, int fq) const {
;     ...
;                     f32x4 cv[2];
; #pragma unroll
;                     for (int bj = 0; bj < 2; ++bj) {
;                         const f32x4 cur = acc[ai][bj][m][n], lo = acc[ai][bj][m > 0 ? m - 1 : 0][n], hi = acc[ai][bj][m < 3 ? m + 1 : 3][n];
;                         f32x4 pv, nv;
; #pragma unroll
;                         for (int idx = 0; idx < 4; ++idx) {
;                             const float y = (fr == 15) ? lo[idx] : cur[idx], z = (fr == 0) ? hi[idx] : cur[idx];
;                             pv[idx] = __int_as_float(__builtin_amdgcn_update_dpp(0, __float_as_int(y), 0x121, 0xf, 0xf, false));
;                             nv[idx] = __int_as_float(__builtin_amdgcn_update_dpp(0, __float_as_int(z), 0x12f, 0xf, 0xf, false));
;                         }
;                         cv[bj] = kc[bj][0] * pv + kc[bj][1] * cur + kc[bj][2] * nv + bc[bj];
;                     }
;                     const int row = row0 + ai * HALF + m * 16;
;                     const bool edge = (m == 0 && fr == 0) || (m == 3 && fr == 15);
;                     if (!edge) { const f32x4 gt = cv[0], vl = cv[1];
;                         u32x2 w; w.x = cvt_pk_bf16(gt[0] * sigmoid_f(gt[0]) * vl[0], gt[1] * sigmoid_f(gt[1]) * vl[1]); w.y = cvt_pk_bf16(gt[2] * sigmoid_f(gt[2]) * vl[2], gt[3] * sigmoid_f(gt[3]) * vl[3]);
;                         *(u32x2*)(ACT + (size_t)row * FF + j4) = w; }
	v_cndmask_b32_e64 v214, 0, v182, s[42:43]
	v_cndmask_b32_e64 v215, 0, v183, s[42:43]
	v_cndmask_b32_e64 v216, 0, v184, s[42:43]
	v_cndmask_b32_e64 v217, 0, v185, s[42:43]
	v_cndmask_b32_e64 v218, 0, v198, s[42:43]
	v_cndmask_b32_e64 v219, 0, v199, s[42:43]
	v_cndmask_b32_e64 v220, 0, v200, s[42:43]
	v_cndmask_b32_e64 v221, 0, v201, s[42:43]
	v_cndmask_b32_e64 v222, 0, v190, s[38:39]
	v_cndmask_b32_e64 v223, 0, v191, s[38:39]
	v_cndmask_b32_e64 v224, 0, v192, s[38:39]
	v_cndmask_b32_e64 v225, 0, v193, s[38:39]
	v_cndmask_b32_e64 v226, 0, v206, s[38:39]
	v_cndmask_b32_e64 v227, 0, v207, s[38:39]
	v_cndmask_b32_e64 v228, 0, v208, s[38:39]
	v_cndmask_b32_e64 v229, 0, v209, s[38:39]
	v_pk_fma_f32 v[230:231], v[126:127], v[186:187], v[194:195]
	v_pk_fma_f32 v[232:233], v[128:129], v[188:189], v[196:197]
	v_pk_fma_f32 v[234:235], v[122:123], v[202:203], v[210:211]
	v_pk_fma_f32 v[236:237], v[124:125], v[204:205], v[212:213]
	v_fmac_f32_dpp v230, v126, v182 row_shr:1 row_mask:0xf bank_mask:0xf
	v_fmac_f32_dpp v231, v127, v183 row_shr:1 row_mask:0xf bank_mask:0xf
	v_fmac_f32_dpp v232, v128, v184 row_shr:1 row_mask:0xf bank_mask:0xf
	v_fmac_f32_dpp v233, v129, v185 row_shr:1 row_mask:0xf bank_mask:0xf
	v_fmac_f32_dpp v234, v122, v198 row_shr:1 row_mask:0xf bank_mask:0xf
	v_fmac_f32_dpp v235, v123, v199 row_shr:1 row_mask:0xf bank_mask:0xf
	v_fmac_f32_dpp v236, v124, v200 row_shr:1 row_mask:0xf bank_mask:0xf
	v_fmac_f32_dpp v237, v125, v201 row_shr:1 row_mask:0xf bank_mask:0xf
	v_fmac_f32_dpp v230, v126, v190 row_shl:1 row_mask:0xf bank_mask:0xf
	v_fmac_f32_dpp v231, v127, v191 row_shl:1 row_mask:0xf bank_mask:0xf
	v_fmac_f32_dpp v232, v128, v192 row_shl:1 row_mask:0xf bank_mask:0xf
	v_fmac_f32_dpp v233, v129, v193 row_shl:1 row_mask:0xf bank_mask:0xf
	v_fmac_f32_dpp v234, v122, v206 row_shl:1 row_mask:0xf bank_mask:0xf
	v_fmac_f32_dpp v235, v123, v207 row_shl:1 row_mask:0xf bank_mask:0xf
	v_fmac_f32_dpp v236, v124, v208 row_shl:1 row_mask:0xf bank_mask:0xf
	v_fmac_f32_dpp v237, v125, v209 row_shl:1 row_mask:0xf bank_mask:0xf
	v_fmac_f32_dpp v230, v118, v222 row_ror:15 row_mask:0xf bank_mask:0xf
	v_fmac_f32_dpp v231, v119, v223 row_ror:15 row_mask:0xf bank_mask:0xf
	v_fmac_f32_dpp v232, v120, v224 row_ror:15 row_mask:0xf bank_mask:0xf
	v_fmac_f32_dpp v233, v121, v225 row_ror:15 row_mask:0xf bank_mask:0xf
	v_fmac_f32_dpp v234, v114, v226 row_ror:15 row_mask:0xf bank_mask:0xf
	v_fmac_f32_dpp v235, v115, v227 row_ror:15 row_mask:0xf bank_mask:0xf
	v_fmac_f32_dpp v236, v116, v228 row_ror:15 row_mask:0xf bank_mask:0xf
	v_fmac_f32_dpp v237, v117, v229 row_ror:15 row_mask:0xf bank_mask:0xf
	v_pk_mul_f32 v[174:175], v[230:231], s[34:35]
	v_pk_mul_f32 v[176:177], v[232:233], s[34:35]
	v_exp_f32_e32 v174, v174
	v_exp_f32_e32 v175, v175
	v_exp_f32_e32 v176, v176
	v_exp_f32_e32 v177, v177
	v_pk_add_f32 v[174:175], v[174:175], s[36:37]
	v_pk_add_f32 v[176:177], v[176:177], s[36:37]
	v_rcp_f32_e32 v174, v174
	v_rcp_f32_e32 v175, v175
	v_rcp_f32_e32 v176, v176
	v_rcp_f32_e32 v177, v177
	v_pk_mul_f32 v[174:175], v[230:231], v[174:175]
	v_pk_mul_f32 v[176:177], v[232:233], v[176:177]
	v_pk_mul_f32 v[174:175], v[174:175], v[234:235]
	v_pk_mul_f32 v[176:177], v[176:177], v[236:237]
	v_cvt_pk_bf16_f32 v130, v174, v175
	v_cvt_pk_bf16_f32 v131, v176, v177
	v_pk_fma_f32 v[230:231], v[118:119], v[186:187], v[194:195]
	v_pk_fma_f32 v[232:233], v[120:121], v[188:189], v[196:197]
	v_pk_fma_f32 v[234:235], v[114:115], v[202:203], v[210:211]
	v_pk_fma_f32 v[236:237], v[116:117], v[204:205], v[212:213]
	v_fmac_f32_dpp v230, v118, v182 row_shr:1 row_mask:0xf bank_mask:0xf
	v_fmac_f32_dpp v231, v119, v183 row_shr:1 row_mask:0xf bank_mask:0xf
	v_fmac_f32_dpp v232, v120, v184 row_shr:1 row_mask:0xf bank_mask:0xf
	v_fmac_f32_dpp v233, v121, v185 row_shr:1 row_mask:0xf bank_mask:0xf
	v_fmac_f32_dpp v234, v114, v198 row_shr:1 row_mask:0xf bank_mask:0xf
	v_fmac_f32_dpp v235, v115, v199 row_shr:1 row_mask:0xf bank_mask:0xf
	v_fmac_f32_dpp v236, v116, v200 row_shr:1 row_mask:0xf bank_mask:0xf
	v_fmac_f32_dpp v237, v117, v201 row_shr:1 row_mask:0xf bank_mask:0xf
	v_fmac_f32_dpp v230, v118, v190 row_shl:1 row_mask:0xf bank_mask:0xf
	v_fmac_f32_dpp v231, v119, v191 row_shl:1 row_mask:0xf bank_mask:0xf
	v_fmac_f32_dpp v232, v120, v192 row_shl:1 row_mask:0xf bank_mask:0xf
	v_fmac_f32_dpp v233, v121, v193 row_shl:1 row_mask:0xf bank_mask:0xf
	v_fmac_f32_dpp v234, v114, v206 row_shl:1 row_mask:0xf bank_mask:0xf
	v_fmac_f32_dpp v235, v115, v207 row_shl:1 row_mask:0xf bank_mask:0xf
	v_fmac_f32_dpp v236, v116, v208 row_shl:1 row_mask:0xf bank_mask:0xf
	v_fmac_f32_dpp v237, v117, v209 row_shl:1 row_mask:0xf bank_mask:0xf
	v_fmac_f32_dpp v230, v126, v214 row_ror:1 row_mask:0xf bank_mask:0xf
	v_fmac_f32_dpp v231, v127, v215 row_ror:1 row_mask:0xf bank_mask:0xf
	v_fmac_f32_dpp v232, v128, v216 row_ror:1 row_mask:0xf bank_mask:0xf
	v_fmac_f32_dpp v233, v129, v217 row_ror:1 row_mask:0xf bank_mask:0xf
	v_fmac_f32_dpp v234, v122, v218 row_ror:1 row_mask:0xf bank_mask:0xf
	v_fmac_f32_dpp v235, v123, v219 row_ror:1 row_mask:0xf bank_mask:0xf
	v_fmac_f32_dpp v236, v124, v220 row_ror:1 row_mask:0xf bank_mask:0xf
	v_fmac_f32_dpp v237, v125, v221 row_ror:1 row_mask:0xf bank_mask:0xf
	v_fmac_f32_dpp v230, v110, v222 row_ror:15 row_mask:0xf bank_mask:0xf
	v_fmac_f32_dpp v231, v111, v223 row_ror:15 row_mask:0xf bank_mask:0xf
	v_fmac_f32_dpp v232, v112, v224 row_ror:15 row_mask:0xf bank_mask:0xf
	v_fmac_f32_dpp v233, v113, v225 row_ror:15 row_mask:0xf bank_mask:0xf
	v_fmac_f32_dpp v234, v102, v226 row_ror:15 row_mask:0xf bank_mask:0xf
	v_fmac_f32_dpp v235, v103, v227 row_ror:15 row_mask:0xf bank_mask:0xf
; __device__ __forceinline__ unsigned cvt_pk_bf16(float lo, float hi) { unsigned r; asm volatile("v_cvt_pk_bf16_f32 %0, %1, %2" : "=v"(r) : "v"(lo), "v"(hi)); return r; }
; __device__ __forceinline__ float fast_rcp(float x) { return __builtin_amdgcn_rcpf(x); }
; __device__ __forceinline__ float fast_exp2(float x) { return __builtin_amdgcn_exp2f(x); }
; __device__ __forceinline__ float sigmoid_f(float x) { return fast_rcp(1.0f + fast_exp2(-1.4426950409f * x)); }
;     __device__ __forceinline__ void operator()(f32x4 (&acc)[2][2][4][2], const Unit& u, int wr, int wc, int fr, int fq) const {
;     ...
;                     f32x4 cv[2];
; #pragma unroll
;                     for (int bj = 0; bj < 2; ++bj) {
;                         const f32x4 cur = acc[ai][bj][m][n], lo = acc[ai][bj][m > 0 ? m - 1 : 0][n], hi = acc[ai][bj][m < 3 ? m + 1 : 3][n];
;                         f32x4 pv, nv;
; #pragma unroll
;                         for (int idx = 0; idx < 4; ++idx) {
;                             const float y = (fr == 15) ? lo[idx] : cur[idx], z = (fr == 0) ? hi[idx] : cur[idx];
;                             pv[idx] = __int_as_float(__builtin_amdgcn_update_dpp(0, __float_as_int(y), 0x121, 0xf, 0xf, false));
;                             nv[idx] = __int_as_float(__builtin_amdgcn_update_dpp(0, __float_as_int(z), 0x12f, 0xf, 0xf, false));
;                         }
;                         cv[bj] = kc[bj][0] * pv + kc[bj][1] * cur + kc[bj][2] * nv + bc[bj];
;                     }
;                     const int row = row0 + ai * HALF + m * 16;
;                     const bool edge = (m == 0 && fr == 0) || (m == 3 && fr == 15);
;                     if (!edge) { const f32x4 gt = cv[0], vl = cv[1];
;                         u32x2 w; w.x = cvt_pk_bf16(gt[0] * sigmoid_f(gt[0]) * vl[0], gt[1] * sigmoid_f(gt[1]) * vl[1]); w.y = cvt_pk_bf16(gt[2] * sigmoid_f(gt[2]) * vl[2], gt[3] * sigmoid_f(gt[3]) * vl[3]);
;                         *(u32x2*)(ACT + (size_t)row * FF + j4) = w; }
	v_fmac_f32_dpp v236, v104, v228 row_ror:15 row_mask:0xf bank_mask:0xf
	v_fmac_f32_dpp v237, v105, v229 row_ror:15 row_mask:0xf bank_mask:0xf
	v_pk_mul_f32 v[174:175], v[230:231], s[34:35]
	v_pk_mul_f32 v[176:177], v[232:233], s[34:35]
	v_exp_f32_e32 v174, v174
	v_exp_f32_e32 v175, v175
	v_exp_f32_e32 v176, v176
	v_exp_f32_e32 v177, v177
	v_pk_add_f32 v[174:175], v[174:175], s[36:37]
	v_pk_add_f32 v[176:177], v[176:177], s[36:37]
	v_rcp_f32_e32 v174, v174
	v_rcp_f32_e32 v175, v175
	v_rcp_f32_e32 v176, v176
	v_rcp_f32_e32 v177, v177
	v_pk_mul_f32 v[174:175], v[230:231], v[174:175]
	v_pk_mul_f32 v[176:177], v[232:233], v[176:177]
	v_pk_mul_f32 v[174:175], v[174:175], v[234:235]
	v_pk_mul_f32 v[176:177], v[176:177], v[236:237]
	v_cvt_pk_bf16_f32 v134, v174, v175
	v_cvt_pk_bf16_f32 v135, v176, v177
	v_pk_fma_f32 v[230:231], v[110:111], v[186:187], v[194:195]
	v_pk_fma_f32 v[232:233], v[112:113], v[188:189], v[196:197]
	v_pk_fma_f32 v[234:235], v[102:103], v[202:203], v[210:211]
	v_pk_fma_f32 v[236:237], v[104:105], v[204:205], v[212:213]
	v_fmac_f32_dpp v230, v110, v182 row_shr:1 row_mask:0xf bank_mask:0xf
	v_fmac_f32_dpp v231, v111, v183 row_shr:1 row_mask:0xf bank_mask:0xf
	v_fmac_f32_dpp v232, v112, v184 row_shr:1 row_mask:0xf bank_mask:0xf
	v_fmac_f32_dpp v233, v113, v185 row_shr:1 row_mask:0xf bank_mask:0xf
	v_fmac_f32_dpp v234, v102, v198 row_shr:1 row_mask:0xf bank_mask:0xf
	v_fmac_f32_dpp v235, v103, v199 row_shr:1 row_mask:0xf bank_mask:0xf
	v_fmac_f32_dpp v236, v104, v200 row_shr:1 row_mask:0xf bank_mask:0xf
	v_fmac_f32_dpp v237, v105, v201 row_shr:1 row_mask:0xf bank_mask:0xf
	v_fmac_f32_dpp v230, v110, v190 row_shl:1 row_mask:0xf bank_mask:0xf
	v_fmac_f32_dpp v231, v111, v191 row_shl:1 row_mask:0xf bank_mask:0xf
	v_fmac_f32_dpp v232, v112, v192 row_shl:1 row_mask:0xf bank_mask:0xf
	v_fmac_f32_dpp v233, v113, v193 row_shl:1 row_mask:0xf bank_mask:0xf
	v_fmac_f32_dpp v234, v102, v206 row_shl:1 row_mask:0xf bank_mask:0xf
	v_fmac_f32_dpp v235, v103, v207 row_shl:1 row_mask:0xf bank_mask:0xf
	v_fmac_f32_dpp v236, v104, v208 row_shl:1 row_mask:0xf bank_mask:0xf
	v_fmac_f32_dpp v237, v105, v209 row_shl:1 row_mask:0xf bank_mask:0xf
	v_fmac_f32_dpp v230, v118, v214 row_ror:1 row_mask:0xf bank_mask:0xf
	v_fmac_f32_dpp v231, v119, v215 row_ror:1 row_mask:0xf bank_mask:0xf
	v_fmac_f32_dpp v232, v120, v216 row_ror:1 row_mask:0xf bank_mask:0xf
	v_fmac_f32_dpp v233, v121, v217 row_ror:1 row_mask:0xf bank_mask:0xf
	v_fmac_f32_dpp v234, v114, v218 row_ror:1 row_mask:0xf bank_mask:0xf
	v_fmac_f32_dpp v235, v115, v219 row_ror:1 row_mask:0xf bank_mask:0xf
	v_fmac_f32_dpp v236, v116, v220 row_ror:1 row_mask:0xf bank_mask:0xf
	v_fmac_f32_dpp v237, v117, v221 row_ror:1 row_mask:0xf bank_mask:0xf
	v_fmac_f32_dpp v230, v106, v222 row_ror:15 row_mask:0xf bank_mask:0xf
	v_fmac_f32_dpp v231, v107, v223 row_ror:15 row_mask:0xf bank_mask:0xf
	v_fmac_f32_dpp v232, v108, v224 row_ror:15 row_mask:0xf bank_mask:0xf
	v_fmac_f32_dpp v233, v109, v225 row_ror:15 row_mask:0xf bank_mask:0xf
	v_fmac_f32_dpp v234, v98, v226 row_ror:15 row_mask:0xf bank_mask:0xf
	v_fmac_f32_dpp v235, v99, v227 row_ror:15 row_mask:0xf bank_mask:0xf
	v_fmac_f32_dpp v236, v100, v228 row_ror:15 row_mask:0xf bank_mask:0xf
	v_fmac_f32_dpp v237, v101, v229 row_ror:15 row_mask:0xf bank_mask:0xf
	v_pk_mul_f32 v[174:175], v[230:231], s[34:35]
	v_pk_mul_f32 v[176:177], v[232:233], s[34:35]
	v_exp_f32_e32 v174, v174
	v_exp_f32_e32 v175, v175
	v_exp_f32_e32 v176, v176
	v_exp_f32_e32 v177, v177
	v_pk_add_f32 v[174:175], v[174:175], s[36:37]
	v_pk_add_f32 v[176:177], v[176:177], s[36:37]
	v_rcp_f32_e32 v174, v174
	v_rcp_f32_e32 v175, v175
	v_rcp_f32_e32 v176, v176
	v_rcp_f32_e32 v177, v177
	v_pk_mul_f32 v[174:175], v[230:231], v[174:175]
	v_pk_mul_f32 v[176:177], v[232:233], v[176:177]
	v_pk_mul_f32 v[174:175], v[174:175], v[234:235]
	v_pk_mul_f32 v[176:177], v[176:177], v[236:237]
	v_cvt_pk_bf16_f32 v138, v174, v175
	v_cvt_pk_bf16_f32 v139, v176, v177
	v_pk_fma_f32 v[230:231], v[106:107], v[186:187], v[194:195]
	v_pk_fma_f32 v[232:233], v[108:109], v[188:189], v[196:197]
	v_pk_fma_f32 v[234:235], v[98:99], v[202:203], v[210:211]
	v_pk_fma_f32 v[236:237], v[100:101], v[204:205], v[212:213]
	v_fmac_f32_dpp v230, v106, v182 row_shr:1 row_mask:0xf bank_mask:0xf
	v_fmac_f32_dpp v231, v107, v183 row_shr:1 row_mask:0xf bank_mask:0xf
	v_fmac_f32_dpp v232, v108, v184 row_shr:1 row_mask:0xf bank_mask:0xf
	v_fmac_f32_dpp v233, v109, v185 row_shr:1 row_mask:0xf bank_mask:0xf
	v_fmac_f32_dpp v234, v98, v198 row_shr:1 row_mask:0xf bank_mask:0xf
	v_fmac_f32_dpp v235, v99, v199 row_shr:1 row_mask:0xf bank_mask:0xf
	v_fmac_f32_dpp v236, v100, v200 row_shr:1 row_mask:0xf bank_mask:0xf
	v_fmac_f32_dpp v237, v101, v201 row_shr:1 row_mask:0xf bank_mask:0xf
	v_fmac_f32_dpp v230, v106, v190 row_shl:1 row_mask:0xf bank_mask:0xf
	v_fmac_f32_dpp v231, v107, v191 row_shl:1 row_mask:0xf bank_mask:0xf
	v_fmac_f32_dpp v232, v108, v192 row_shl:1 row_mask:0xf bank_mask:0xf
	v_fmac_f32_dpp v233, v109, v193 row_shl:1 row_mask:0xf bank_mask:0xf
	v_fmac_f32_dpp v234, v98, v206 row_shl:1 row_mask:0xf bank_mask:0xf
	v_fmac_f32_dpp v235, v99, v207 row_shl:1 row_mask:0xf bank_mask:0xf
	v_fmac_f32_dpp v236, v100, v208 row_shl:1 row_mask:0xf bank_mask:0xf
	v_fmac_f32_dpp v237, v101, v209 row_shl:1 row_mask:0xf bank_mask:0xf
	v_fmac_f32_dpp v230, v110, v214 row_ror:1 row_mask:0xf bank_mask:0xf
	v_fmac_f32_dpp v231, v111, v215 row_ror:1 row_mask:0xf bank_mask:0xf
	v_fmac_f32_dpp v232, v112, v216 row_ror:1 row_mask:0xf bank_mask:0xf
	v_fmac_f32_dpp v233, v113, v217 row_ror:1 row_mask:0xf bank_mask:0xf
	v_fmac_f32_dpp v234, v102, v218 row_ror:1 row_mask:0xf bank_mask:0xf
; __device__ __forceinline__ unsigned cvt_pk_bf16(float lo, float hi) { unsigned r; asm volatile("v_cvt_pk_bf16_f32 %0, %1, %2" : "=v"(r) : "v"(lo), "v"(hi)); return r; }
; __device__ __forceinline__ float sigmoid_f(float x) { return fast_rcp(1.0f + fast_exp2(-1.4426950409f * x)); }
;     __device__ __forceinline__ void operator()(f32x4 (&acc)[2][2][4][2], const Unit& u, int wr, int wc, int fr, int fq) const {
;     ...
;         for (int n = 0; n < 2; ++n) {
;             const int j4 = u.pn * 128 + wc * 32 + 8 * fq + 4 * n;
;             f32x4 kc[2][3], bc[2];
; #pragma unroll
;             for (int bj = 0; bj < 2; ++bj) { bc[bj] = *(const f32x4*)(cb + bj * FF + j4);
; #pragma unroll
;                 for (int w = 0; w < 3; ++w) kc[bj][w] = *(const f32x4*)(ck + w * NUP + bj * FF + j4); }
; #pragma unroll
;             for (int ai = 0; ai < 2; ++ai) {
;                 const int grp = u.pm * 4 + ai * 2 + wr;
; #pragma unroll
;                 for (int m = 0; m < 4; ++m) {
;                     f32x4 cv[2];
; #pragma unroll
;                     for (int bj = 0; bj < 2; ++bj) {
;                         const f32x4 cur = acc[ai][bj][m][n], lo = acc[ai][bj][m > 0 ? m - 1 : 0][n], hi = acc[ai][bj][m < 3 ? m + 1 : 3][n];
;                         f32x4 pv, nv;
; #pragma unroll
;                         for (int idx = 0; idx < 4; ++idx) {
;                             const float y = (fr == 15) ? lo[idx] : cur[idx], z = (fr == 0) ? hi[idx] : cur[idx];
;                             pv[idx] = __int_as_float(__builtin_amdgcn_update_dpp(0, __float_as_int(y), 0x121, 0xf, 0xf, false));
;                             nv[idx] = __int_as_float(__builtin_amdgcn_update_dpp(0, __float_as_int(z), 0x12f, 0xf, 0xf, false));
;                         }
;                         cv[bj] = kc[bj][0] * pv + kc[bj][1] * cur + kc[bj][2] * nv + bc[bj];
;                     }
;                     const int row = row0 + ai * HALF + m * 16;
;                     const bool edge = (m == 0 && fr == 0) || (m == 3 && fr == 15);
;                     if (!edge) { const f32x4 gt = cv[0], vl = cv[1];
;                         u32x2 w; w.x = cvt_pk_bf16(gt[0] * sigmoid_f(gt[0]) * vl[0], gt[1] * sigmoid_f(gt[1]) * vl[1]); w.y = cvt_pk_bf16(gt[2] * sigmoid_f(gt[2]) * vl[2], gt[3] * sigmoid_f(gt[3]) * vl[3]);
;                         *(u32x2*)(ACT + (size_t)row * FF + j4) = w; }
	v_fmac_f32_dpp v235, v103, v219 row_ror:1 row_mask:0xf bank_mask:0xf
	v_fmac_f32_dpp v236, v104, v220 row_ror:1 row_mask:0xf bank_mask:0xf
	v_fmac_f32_dpp v237, v105, v221 row_ror:1 row_mask:0xf bank_mask:0xf
	v_pk_mul_f32 v[174:175], v[230:231], s[34:35]
	v_pk_mul_f32 v[176:177], v[232:233], s[34:35]
	v_exp_f32_e32 v174, v174
	v_exp_f32_e32 v175, v175
	v_exp_f32_e32 v176, v176
	v_exp_f32_e32 v177, v177
	v_pk_add_f32 v[174:175], v[174:175], s[36:37]
	v_pk_add_f32 v[176:177], v[176:177], s[36:37]
	v_rcp_f32_e32 v174, v174
	v_rcp_f32_e32 v175, v175
	v_rcp_f32_e32 v176, v176
	v_rcp_f32_e32 v177, v177
	v_pk_mul_f32 v[174:175], v[230:231], v[174:175]
	v_pk_mul_f32 v[176:177], v[232:233], v[176:177]
	v_pk_mul_f32 v[174:175], v[174:175], v[234:235]
	v_pk_mul_f32 v[176:177], v[176:177], v[236:237]
	v_cvt_pk_bf16_f32 v142, v174, v175
	v_cvt_pk_bf16_f32 v143, v176, v177
	v_add_u32_e32 v174, 0x5600, v242
	v_add_u32_e32 v175, 0xac00, v242
	v_add_u32_e32 v176, 0x10200, v242
	v_add_u32_e32 v177, 0x15800, v242
	v_add_u32_e32 v239, 0x1ae00, v242
	global_load_dwordx4 v[126:129], v242, s[18:19] offset:16
	global_load_dwordx4 v[118:121], v175, s[18:19] offset:16
	global_load_dwordx4 v[110:113], v177, s[18:19] offset:16
	global_load_dwordx4 v[106:109], v242, s[20:21] offset:16
	global_load_dwordx4 v[122:125], v174, s[18:19] offset:16
	global_load_dwordx4 v[114:117], v176, s[18:19] offset:16
	global_load_dwordx4 v[102:105], v239, s[18:19] offset:16
	global_load_dwordx4 v[98:101], v174, s[20:21] offset:16
	v_pk_fma_f32 v[230:231], v[94:95], v[186:187], v[194:195]
	v_pk_fma_f32 v[232:233], v[96:97], v[188:189], v[196:197]
	v_pk_fma_f32 v[234:235], v[86:87], v[202:203], v[210:211]
	v_pk_fma_f32 v[236:237], v[88:89], v[204:205], v[212:213]
	v_fmac_f32_dpp v230, v94, v182 row_shr:1 row_mask:0xf bank_mask:0xf
	v_fmac_f32_dpp v231, v95, v183 row_shr:1 row_mask:0xf bank_mask:0xf
	v_fmac_f32_dpp v232, v96, v184 row_shr:1 row_mask:0xf bank_mask:0xf
	v_fmac_f32_dpp v233, v97, v185 row_shr:1 row_mask:0xf bank_mask:0xf
	v_fmac_f32_dpp v234, v86, v198 row_shr:1 row_mask:0xf bank_mask:0xf
	v_fmac_f32_dpp v235, v87, v199 row_shr:1 row_mask:0xf bank_mask:0xf
	v_fmac_f32_dpp v236, v88, v200 row_shr:1 row_mask:0xf bank_mask:0xf
	v_fmac_f32_dpp v237, v89, v201 row_shr:1 row_mask:0xf bank_mask:0xf
	v_fmac_f32_dpp v230, v94, v190 row_shl:1 row_mask:0xf bank_mask:0xf
	v_fmac_f32_dpp v231, v95, v191 row_shl:1 row_mask:0xf bank_mask:0xf
	v_fmac_f32_dpp v232, v96, v192 row_shl:1 row_mask:0xf bank_mask:0xf
	v_fmac_f32_dpp v233, v97, v193 row_shl:1 row_mask:0xf bank_mask:0xf
	v_fmac_f32_dpp v234, v86, v206 row_shl:1 row_mask:0xf bank_mask:0xf
	v_fmac_f32_dpp v235, v87, v207 row_shl:1 row_mask:0xf bank_mask:0xf
	v_fmac_f32_dpp v236, v88, v208 row_shl:1 row_mask:0xf bank_mask:0xf
	v_fmac_f32_dpp v237, v89, v209 row_shl:1 row_mask:0xf bank_mask:0xf
	v_fmac_f32_dpp v230, v90, v222 row_ror:15 row_mask:0xf bank_mask:0xf
	v_fmac_f32_dpp v231, v91, v223 row_ror:15 row_mask:0xf bank_mask:0xf
	v_fmac_f32_dpp v232, v92, v224 row_ror:15 row_mask:0xf bank_mask:0xf
	v_fmac_f32_dpp v233, v93, v225 row_ror:15 row_mask:0xf bank_mask:0xf
	v_fmac_f32_dpp v234, v82, v226 row_ror:15 row_mask:0xf bank_mask:0xf
	v_fmac_f32_dpp v235, v83, v227 row_ror:15 row_mask:0xf bank_mask:0xf
	v_fmac_f32_dpp v236, v84, v228 row_ror:15 row_mask:0xf bank_mask:0xf
	v_fmac_f32_dpp v237, v85, v229 row_ror:15 row_mask:0xf bank_mask:0xf
	v_pk_mul_f32 v[174:175], v[230:231], s[34:35]
	v_pk_mul_f32 v[176:177], v[232:233], s[34:35]
	v_exp_f32_e32 v174, v174
	v_exp_f32_e32 v175, v175
	v_exp_f32_e32 v176, v176
	v_exp_f32_e32 v177, v177
	v_pk_add_f32 v[174:175], v[174:175], s[36:37]
	v_pk_add_f32 v[176:177], v[176:177], s[36:37]
	v_rcp_f32_e32 v174, v174
	v_rcp_f32_e32 v175, v175
	v_rcp_f32_e32 v176, v176
	v_rcp_f32_e32 v177, v177
	v_pk_mul_f32 v[174:175], v[230:231], v[174:175]
	v_pk_mul_f32 v[176:177], v[232:233], v[176:177]
	v_pk_mul_f32 v[174:175], v[174:175], v[234:235]
	v_pk_mul_f32 v[176:177], v[176:177], v[236:237]
	v_cvt_pk_bf16_f32 v178, v174, v175
	v_cvt_pk_bf16_f32 v179, v176, v177
	v_pk_fma_f32 v[230:231], v[90:91], v[186:187], v[194:195]
	v_pk_fma_f32 v[232:233], v[92:93], v[188:189], v[196:197]
	v_pk_fma_f32 v[234:235], v[82:83], v[202:203], v[210:211]
	v_pk_fma_f32 v[236:237], v[84:85], v[204:205], v[212:213]
	v_fmac_f32_dpp v230, v90, v182 row_shr:1 row_mask:0xf bank_mask:0xf
	v_fmac_f32_dpp v231, v91, v183 row_shr:1 row_mask:0xf bank_mask:0xf
	v_fmac_f32_dpp v232, v92, v184 row_shr:1 row_mask:0xf bank_mask:0xf
	v_fmac_f32_dpp v233, v93, v185 row_shr:1 row_mask:0xf bank_mask:0xf
	v_fmac_f32_dpp v234, v82, v198 row_shr:1 row_mask:0xf bank_mask:0xf
	v_fmac_f32_dpp v235, v83, v199 row_shr:1 row_mask:0xf bank_mask:0xf
	v_fmac_f32_dpp v236, v84, v200 row_shr:1 row_mask:0xf bank_mask:0xf
	v_fmac_f32_dpp v237, v85, v201 row_shr:1 row_mask:0xf bank_mask:0xf
	v_fmac_f32_dpp v230, v90, v190 row_shl:1 row_mask:0xf bank_mask:0xf
	v_fmac_f32_dpp v231, v91, v191 row_shl:1 row_mask:0xf bank_mask:0xf
	v_fmac_f32_dpp v232, v92, v192 row_shl:1 row_mask:0xf bank_mask:0xf
	v_fmac_f32_dpp v233, v93, v193 row_shl:1 row_mask:0xf bank_mask:0xf
	v_fmac_f32_dpp v234, v82, v206 row_shl:1 row_mask:0xf bank_mask:0xf
	v_fmac_f32_dpp v235, v83, v207 row_shl:1 row_mask:0xf bank_mask:0xf
	v_fmac_f32_dpp v236, v84, v208 row_shl:1 row_mask:0xf bank_mask:0xf
	v_fmac_f32_dpp v237, v85, v209 row_shl:1 row_mask:0xf bank_mask:0xf
	v_fmac_f32_dpp v230, v94, v214 row_ror:1 row_mask:0xf bank_mask:0xf
	v_fmac_f32_dpp v231, v95, v215 row_ror:1 row_mask:0xf bank_mask:0xf
	v_fmac_f32_dpp v232, v96, v216 row_ror:1 row_mask:0xf bank_mask:0xf
; __device__ __forceinline__ unsigned cvt_pk_bf16(float lo, float hi) { unsigned r; asm volatile("v_cvt_pk_bf16_f32 %0, %1, %2" : "=v"(r) : "v"(lo), "v"(hi)); return r; }
; __device__ __forceinline__ float sigmoid_f(float x) { return fast_rcp(1.0f + fast_exp2(-1.4426950409f * x)); }
;     __device__ __forceinline__ void operator()(f32x4 (&acc)[2][2][4][2], const Unit& u, int wr, int wc, int fr, int fq) const {
;     ...
;                     f32x4 cv[2];
; #pragma unroll
;                     for (int bj = 0; bj < 2; ++bj) {
;                         const f32x4 cur = acc[ai][bj][m][n], lo = acc[ai][bj][m > 0 ? m - 1 : 0][n], hi = acc[ai][bj][m < 3 ? m + 1 : 3][n];
;                         f32x4 pv, nv;
; #pragma unroll
;                         for (int idx = 0; idx < 4; ++idx) {
;                             const float y = (fr == 15) ? lo[idx] : cur[idx], z = (fr == 0) ? hi[idx] : cur[idx];
;                             pv[idx] = __int_as_float(__builtin_amdgcn_update_dpp(0, __float_as_int(y), 0x121, 0xf, 0xf, false));
;                             nv[idx] = __int_as_float(__builtin_amdgcn_update_dpp(0, __float_as_int(z), 0x12f, 0xf, 0xf, false));
;                         }
;                         cv[bj] = kc[bj][0] * pv + kc[bj][1] * cur + kc[bj][2] * nv + bc[bj];
;                     }
;                     const int row = row0 + ai * HALF + m * 16;
;                     const bool edge = (m == 0 && fr == 0) || (m == 3 && fr == 15);
;                     if (!edge) { const f32x4 gt = cv[0], vl = cv[1];
;                         u32x2 w; w.x = cvt_pk_bf16(gt[0] * sigmoid_f(gt[0]) * vl[0], gt[1] * sigmoid_f(gt[1]) * vl[1]); w.y = cvt_pk_bf16(gt[2] * sigmoid_f(gt[2]) * vl[2], gt[3] * sigmoid_f(gt[3]) * vl[3]);
;                         *(u32x2*)(ACT + (size_t)row * FF + j4) = w; }
	v_fmac_f32_dpp v233, v97, v217 row_ror:1 row_mask:0xf bank_mask:0xf
	v_fmac_f32_dpp v234, v86, v218 row_ror:1 row_mask:0xf bank_mask:0xf
	v_fmac_f32_dpp v235, v87, v219 row_ror:1 row_mask:0xf bank_mask:0xf
	v_fmac_f32_dpp v236, v88, v220 row_ror:1 row_mask:0xf bank_mask:0xf
	v_fmac_f32_dpp v237, v89, v221 row_ror:1 row_mask:0xf bank_mask:0xf
	v_fmac_f32_dpp v230, v78, v222 row_ror:15 row_mask:0xf bank_mask:0xf
	v_fmac_f32_dpp v231, v79, v223 row_ror:15 row_mask:0xf bank_mask:0xf
	v_fmac_f32_dpp v232, v80, v224 row_ror:15 row_mask:0xf bank_mask:0xf
	v_fmac_f32_dpp v233, v81, v225 row_ror:15 row_mask:0xf bank_mask:0xf
	v_fmac_f32_dpp v234, v70, v226 row_ror:15 row_mask:0xf bank_mask:0xf
	v_fmac_f32_dpp v235, v71, v227 row_ror:15 row_mask:0xf bank_mask:0xf
	v_fmac_f32_dpp v236, v72, v228 row_ror:15 row_mask:0xf bank_mask:0xf
	v_fmac_f32_dpp v237, v73, v229 row_ror:15 row_mask:0xf bank_mask:0xf
	v_pk_mul_f32 v[174:175], v[230:231], s[34:35]
	v_pk_mul_f32 v[176:177], v[232:233], s[34:35]
	v_exp_f32_e32 v174, v174
	v_exp_f32_e32 v175, v175
	v_exp_f32_e32 v176, v176
	v_exp_f32_e32 v177, v177
	v_pk_add_f32 v[174:175], v[174:175], s[36:37]
	v_pk_add_f32 v[176:177], v[176:177], s[36:37]
	v_rcp_f32_e32 v174, v174
	v_rcp_f32_e32 v175, v175
	v_rcp_f32_e32 v176, v176
	v_rcp_f32_e32 v177, v177
	v_pk_mul_f32 v[174:175], v[230:231], v[174:175]
	v_pk_mul_f32 v[176:177], v[232:233], v[176:177]
	v_pk_mul_f32 v[174:175], v[174:175], v[234:235]
	v_pk_mul_f32 v[176:177], v[176:177], v[236:237]
	v_cvt_pk_bf16_f32 v94, v174, v175
	v_cvt_pk_bf16_f32 v95, v176, v177
	v_pk_fma_f32 v[230:231], v[78:79], v[186:187], v[194:195]
	v_pk_fma_f32 v[232:233], v[80:81], v[188:189], v[196:197]
	v_pk_fma_f32 v[234:235], v[70:71], v[202:203], v[210:211]
	v_pk_fma_f32 v[236:237], v[72:73], v[204:205], v[212:213]
	v_fmac_f32_dpp v230, v78, v182 row_shr:1 row_mask:0xf bank_mask:0xf
	v_fmac_f32_dpp v231, v79, v183 row_shr:1 row_mask:0xf bank_mask:0xf
	v_fmac_f32_dpp v232, v80, v184 row_shr:1 row_mask:0xf bank_mask:0xf
	v_fmac_f32_dpp v233, v81, v185 row_shr:1 row_mask:0xf bank_mask:0xf
	v_fmac_f32_dpp v234, v70, v198 row_shr:1 row_mask:0xf bank_mask:0xf
	v_fmac_f32_dpp v235, v71, v199 row_shr:1 row_mask:0xf bank_mask:0xf
	v_fmac_f32_dpp v236, v72, v200 row_shr:1 row_mask:0xf bank_mask:0xf
	v_fmac_f32_dpp v237, v73, v201 row_shr:1 row_mask:0xf bank_mask:0xf
	v_fmac_f32_dpp v230, v78, v190 row_shl:1 row_mask:0xf bank_mask:0xf
	v_fmac_f32_dpp v231, v79, v191 row_shl:1 row_mask:0xf bank_mask:0xf
	v_fmac_f32_dpp v232, v80, v192 row_shl:1 row_mask:0xf bank_mask:0xf
	v_fmac_f32_dpp v233, v81, v193 row_shl:1 row_mask:0xf bank_mask:0xf
	v_fmac_f32_dpp v234, v70, v206 row_shl:1 row_mask:0xf bank_mask:0xf
	v_fmac_f32_dpp v235, v71, v207 row_shl:1 row_mask:0xf bank_mask:0xf
	v_fmac_f32_dpp v236, v72, v208 row_shl:1 row_mask:0xf bank_mask:0xf
	v_fmac_f32_dpp v237, v73, v209 row_shl:1 row_mask:0xf bank_mask:0xf
	v_fmac_f32_dpp v230, v90, v214 row_ror:1 row_mask:0xf bank_mask:0xf
	v_fmac_f32_dpp v231, v91, v215 row_ror:1 row_mask:0xf bank_mask:0xf
	v_fmac_f32_dpp v232, v92, v216 row_ror:1 row_mask:0xf bank_mask:0xf
	v_fmac_f32_dpp v233, v93, v217 row_ror:1 row_mask:0xf bank_mask:0xf
	v_fmac_f32_dpp v234, v82, v218 row_ror:1 row_mask:0xf bank_mask:0xf
	v_fmac_f32_dpp v235, v83, v219 row_ror:1 row_mask:0xf bank_mask:0xf
	v_fmac_f32_dpp v236, v84, v220 row_ror:1 row_mask:0xf bank_mask:0xf
	v_fmac_f32_dpp v237, v85, v221 row_ror:1 row_mask:0xf bank_mask:0xf
	v_fmac_f32_dpp v230, v74, v222 row_ror:15 row_mask:0xf bank_mask:0xf
	v_fmac_f32_dpp v231, v75, v223 row_ror:15 row_mask:0xf bank_mask:0xf
	v_fmac_f32_dpp v232, v76, v224 row_ror:15 row_mask:0xf bank_mask:0xf
	v_fmac_f32_dpp v233, v77, v225 row_ror:15 row_mask:0xf bank_mask:0xf
	v_fmac_f32_dpp v234, v66, v226 row_ror:15 row_mask:0xf bank_mask:0xf
	v_fmac_f32_dpp v235, v67, v227 row_ror:15 row_mask:0xf bank_mask:0xf
	v_fmac_f32_dpp v236, v68, v228 row_ror:15 row_mask:0xf bank_mask:0xf
	v_fmac_f32_dpp v237, v69, v229 row_ror:15 row_mask:0xf bank_mask:0xf
	v_pk_mul_f32 v[174:175], v[230:231], s[34:35]
	v_pk_mul_f32 v[176:177], v[232:233], s[34:35]
	v_exp_f32_e32 v174, v174
	v_exp_f32_e32 v175, v175
	v_exp_f32_e32 v176, v176
	v_exp_f32_e32 v177, v177
	v_pk_add_f32 v[174:175], v[174:175], s[36:37]
	v_pk_add_f32 v[176:177], v[176:177], s[36:37]
	v_rcp_f32_e32 v174, v174
	v_rcp_f32_e32 v175, v175
	v_rcp_f32_e32 v176, v176
	v_rcp_f32_e32 v177, v177
	v_pk_mul_f32 v[174:175], v[230:231], v[174:175]
	v_pk_mul_f32 v[176:177], v[232:233], v[176:177]
	v_pk_mul_f32 v[174:175], v[174:175], v[234:235]
	v_pk_mul_f32 v[176:177], v[176:177], v[236:237]
	v_cvt_pk_bf16_f32 v90, v174, v175
	v_cvt_pk_bf16_f32 v91, v176, v177
	v_pk_fma_f32 v[230:231], v[74:75], v[186:187], v[194:195]
	v_pk_fma_f32 v[232:233], v[76:77], v[188:189], v[196:197]
	v_pk_fma_f32 v[234:235], v[66:67], v[202:203], v[210:211]
	v_pk_fma_f32 v[236:237], v[68:69], v[204:205], v[212:213]
	v_fmac_f32_dpp v230, v74, v182 row_shr:1 row_mask:0xf bank_mask:0xf
	v_fmac_f32_dpp v231, v75, v183 row_shr:1 row_mask:0xf bank_mask:0xf
	v_fmac_f32_dpp v232, v76, v184 row_shr:1 row_mask:0xf bank_mask:0xf
	v_fmac_f32_dpp v233, v77, v185 row_shr:1 row_mask:0xf bank_mask:0xf
	v_fmac_f32_dpp v234, v66, v198 row_shr:1 row_mask:0xf bank_mask:0xf
	v_fmac_f32_dpp v235, v67, v199 row_shr:1 row_mask:0xf bank_mask:0xf
	v_fmac_f32_dpp v236, v68, v200 row_shr:1 row_mask:0xf bank_mask:0xf
	v_fmac_f32_dpp v237, v69, v201 row_shr:1 row_mask:0xf bank_mask:0xf
	v_fmac_f32_dpp v230, v74, v190 row_shl:1 row_mask:0xf bank_mask:0xf
	v_fmac_f32_dpp v231, v75, v191 row_shl:1 row_mask:0xf bank_mask:0xf
; __device__ __forceinline__ unsigned cvt_pk_bf16(float lo, float hi) { unsigned r; asm volatile("v_cvt_pk_bf16_f32 %0, %1, %2" : "=v"(r) : "v"(lo), "v"(hi)); return r; }
; __device__ __forceinline__ float sigmoid_f(float x) { return fast_rcp(1.0f + fast_exp2(-1.4426950409f * x)); }
;     __device__ __forceinline__ void operator()(f32x4 (&acc)[2][2][4][2], const Unit& u, int wr, int wc, int fr, int fq) const {
;     ...
;             for (int ai = 0; ai < 2; ++ai) {
;                 const int grp = u.pm * 4 + ai * 2 + wr;
; #pragma unroll
;                 for (int m = 0; m < 4; ++m) {
;                     f32x4 cv[2];
; #pragma unroll
;                     for (int bj = 0; bj < 2; ++bj) {
;                         const f32x4 cur = acc[ai][bj][m][n], lo = acc[ai][bj][m > 0 ? m - 1 : 0][n], hi = acc[ai][bj][m < 3 ? m + 1 : 3][n];
;                         f32x4 pv, nv;
; #pragma unroll
;                         for (int idx = 0; idx < 4; ++idx) {
;                             const float y = (fr == 15) ? lo[idx] : cur[idx], z = (fr == 0) ? hi[idx] : cur[idx];
;                             pv[idx] = __int_as_float(__builtin_amdgcn_update_dpp(0, __float_as_int(y), 0x121, 0xf, 0xf, false));
;                             nv[idx] = __int_as_float(__builtin_amdgcn_update_dpp(0, __float_as_int(z), 0x12f, 0xf, 0xf, false));
;                         }
;                         cv[bj] = kc[bj][0] * pv + kc[bj][1] * cur + kc[bj][2] * nv + bc[bj];
;                     }
;                     const int row = row0 + ai * HALF + m * 16;
;                     const bool edge = (m == 0 && fr == 0) || (m == 3 && fr == 15);
;                     if (!edge) { const f32x4 gt = cv[0], vl = cv[1];
;                         u32x2 w; w.x = cvt_pk_bf16(gt[0] * sigmoid_f(gt[0]) * vl[0], gt[1] * sigmoid_f(gt[1]) * vl[1]); w.y = cvt_pk_bf16(gt[2] * sigmoid_f(gt[2]) * vl[2], gt[3] * sigmoid_f(gt[3]) * vl[3]);
;                         *(u32x2*)(ACT + (size_t)row * FF + j4) = w; }
	v_fmac_f32_dpp v232, v76, v192 row_shl:1 row_mask:0xf bank_mask:0xf
	v_fmac_f32_dpp v233, v77, v193 row_shl:1 row_mask:0xf bank_mask:0xf
	v_fmac_f32_dpp v234, v66, v206 row_shl:1 row_mask:0xf bank_mask:0xf
	v_fmac_f32_dpp v235, v67, v207 row_shl:1 row_mask:0xf bank_mask:0xf
	v_fmac_f32_dpp v236, v68, v208 row_shl:1 row_mask:0xf bank_mask:0xf
	v_fmac_f32_dpp v237, v69, v209 row_shl:1 row_mask:0xf bank_mask:0xf
	v_fmac_f32_dpp v230, v78, v214 row_ror:1 row_mask:0xf bank_mask:0xf
	v_fmac_f32_dpp v231, v79, v215 row_ror:1 row_mask:0xf bank_mask:0xf
	v_fmac_f32_dpp v232, v80, v216 row_ror:1 row_mask:0xf bank_mask:0xf
	v_fmac_f32_dpp v233, v81, v217 row_ror:1 row_mask:0xf bank_mask:0xf
	v_fmac_f32_dpp v234, v70, v218 row_ror:1 row_mask:0xf bank_mask:0xf
	v_fmac_f32_dpp v235, v71, v219 row_ror:1 row_mask:0xf bank_mask:0xf
	v_fmac_f32_dpp v236, v72, v220 row_ror:1 row_mask:0xf bank_mask:0xf
	v_fmac_f32_dpp v237, v73, v221 row_ror:1 row_mask:0xf bank_mask:0xf
	v_pk_mul_f32 v[174:175], v[230:231], s[34:35]
	v_pk_mul_f32 v[176:177], v[232:233], s[34:35]
	v_exp_f32_e32 v174, v174
	v_exp_f32_e32 v175, v175
	v_exp_f32_e32 v176, v176
	v_exp_f32_e32 v177, v177
	v_pk_add_f32 v[174:175], v[174:175], s[36:37]
	v_pk_add_f32 v[176:177], v[176:177], s[36:37]
	v_rcp_f32_e32 v174, v174
	v_rcp_f32_e32 v175, v175
	v_rcp_f32_e32 v176, v176
	v_rcp_f32_e32 v177, v177
	v_pk_mul_f32 v[174:175], v[230:231], v[174:175]
	v_pk_mul_f32 v[176:177], v[232:233], v[176:177]
	v_pk_mul_f32 v[174:175], v[174:175], v[234:235]
	v_pk_mul_f32 v[176:177], v[176:177], v[236:237]
	v_cvt_pk_bf16_f32 v78, v174, v175
	v_cvt_pk_bf16_f32 v79, v176, v177
	s_waitcnt vmcnt(0)
	v_cndmask_b32_e64 v214, 0, v126, s[42:43]
	v_cndmask_b32_e64 v215, 0, v127, s[42:43]
	v_cndmask_b32_e64 v216, 0, v128, s[42:43]
	v_cndmask_b32_e64 v217, 0, v129, s[42:43]
	v_cndmask_b32_e64 v218, 0, v122, s[42:43]
	v_cndmask_b32_e64 v219, 0, v123, s[42:43]
	v_cndmask_b32_e64 v220, 0, v124, s[42:43]
	v_cndmask_b32_e64 v221, 0, v125, s[42:43]
	v_cndmask_b32_e64 v222, 0, v110, s[38:39]
	v_cndmask_b32_e64 v223, 0, v111, s[38:39]
	v_cndmask_b32_e64 v224, 0, v112, s[38:39]
	v_cndmask_b32_e64 v225, 0, v113, s[38:39]
	v_cndmask_b32_e64 v226, 0, v102, s[38:39]
	v_cndmask_b32_e64 v227, 0, v103, s[38:39]
	v_cndmask_b32_e64 v228, 0, v104, s[38:39]
	v_cndmask_b32_e64 v229, 0, v105, s[38:39]
	v_pk_fma_f32 v[230:231], v[62:63], v[118:119], v[106:107]
	v_pk_fma_f32 v[232:233], v[64:65], v[120:121], v[108:109]
	v_pk_fma_f32 v[234:235], v[54:55], v[114:115], v[98:99]
	v_pk_fma_f32 v[236:237], v[56:57], v[116:117], v[100:101]
	v_fmac_f32_dpp v230, v62, v126 row_shr:1 row_mask:0xf bank_mask:0xf
	v_fmac_f32_dpp v231, v63, v127 row_shr:1 row_mask:0xf bank_mask:0xf
	v_fmac_f32_dpp v232, v64, v128 row_shr:1 row_mask:0xf bank_mask:0xf
	v_fmac_f32_dpp v233, v65, v129 row_shr:1 row_mask:0xf bank_mask:0xf
	v_fmac_f32_dpp v234, v54, v122 row_shr:1 row_mask:0xf bank_mask:0xf
	v_fmac_f32_dpp v235, v55, v123 row_shr:1 row_mask:0xf bank_mask:0xf
	v_fmac_f32_dpp v236, v56, v124 row_shr:1 row_mask:0xf bank_mask:0xf
	v_fmac_f32_dpp v237, v57, v125 row_shr:1 row_mask:0xf bank_mask:0xf
	v_fmac_f32_dpp v230, v62, v110 row_shl:1 row_mask:0xf bank_mask:0xf
	v_fmac_f32_dpp v231, v63, v111 row_shl:1 row_mask:0xf bank_mask:0xf
	v_fmac_f32_dpp v232, v64, v112 row_shl:1 row_mask:0xf bank_mask:0xf
	v_fmac_f32_dpp v233, v65, v113 row_shl:1 row_mask:0xf bank_mask:0xf
	v_fmac_f32_dpp v234, v54, v102 row_shl:1 row_mask:0xf bank_mask:0xf
	v_fmac_f32_dpp v235, v55, v103 row_shl:1 row_mask:0xf bank_mask:0xf
	v_fmac_f32_dpp v236, v56, v104 row_shl:1 row_mask:0xf bank_mask:0xf
	v_fmac_f32_dpp v237, v57, v105 row_shl:1 row_mask:0xf bank_mask:0xf
	v_fmac_f32_dpp v230, v58, v222 row_ror:15 row_mask:0xf bank_mask:0xf
	v_fmac_f32_dpp v231, v59, v223 row_ror:15 row_mask:0xf bank_mask:0xf
	v_fmac_f32_dpp v232, v60, v224 row_ror:15 row_mask:0xf bank_mask:0xf
	v_fmac_f32_dpp v233, v61, v225 row_ror:15 row_mask:0xf bank_mask:0xf
	v_fmac_f32_dpp v234, v50, v226 row_ror:15 row_mask:0xf bank_mask:0xf
	v_fmac_f32_dpp v235, v51, v227 row_ror:15 row_mask:0xf bank_mask:0xf
	v_fmac_f32_dpp v236, v52, v228 row_ror:15 row_mask:0xf bank_mask:0xf
	v_fmac_f32_dpp v237, v53, v229 row_ror:15 row_mask:0xf bank_mask:0xf
	v_pk_mul_f32 v[174:175], v[230:231], s[34:35]
	v_pk_mul_f32 v[176:177], v[232:233], s[34:35]
	v_exp_f32_e32 v174, v174
	v_exp_f32_e32 v175, v175
	v_exp_f32_e32 v176, v176
	v_exp_f32_e32 v177, v177
	v_pk_add_f32 v[174:175], v[174:175], s[36:37]
	v_pk_add_f32 v[176:177], v[176:177], s[36:37]
	v_rcp_f32_e32 v174, v174
	v_rcp_f32_e32 v175, v175
	v_rcp_f32_e32 v176, v176
	v_rcp_f32_e32 v177, v177
	v_pk_mul_f32 v[174:175], v[230:231], v[174:175]
	v_pk_mul_f32 v[176:177], v[232:233], v[176:177]
	v_pk_mul_f32 v[174:175], v[174:175], v[234:235]
	v_pk_mul_f32 v[176:177], v[176:177], v[236:237]
	v_cvt_pk_bf16_f32 v132, v174, v175
	v_cvt_pk_bf16_f32 v133, v176, v177
	s_and_saveexec_b64 s[16:17], s[44:45]
	global_store_dwordx4 v238, v[130:133], s[30:31]
	s_or_b64 exec, exec, s[16:17]
	v_pk_fma_f32 v[230:231], v[58:59], v[118:119], v[106:107]
	v_pk_fma_f32 v[232:233], v[60:61], v[120:121], v[108:109]
	v_pk_fma_f32 v[234:235], v[50:51], v[114:115], v[98:99]
	v_pk_fma_f32 v[236:237], v[52:53], v[116:117], v[100:101]
	v_fmac_f32_dpp v230, v58, v126 row_shr:1 row_mask:0xf bank_mask:0xf
	v_fmac_f32_dpp v231, v59, v127 row_shr:1 row_mask:0xf bank_mask:0xf
	v_fmac_f32_dpp v232, v60, v128 row_shr:1 row_mask:0xf bank_mask:0xf
	v_fmac_f32_dpp v233, v61, v129 row_shr:1 row_mask:0xf bank_mask:0xf
	v_fmac_f32_dpp v234, v50, v122 row_shr:1 row_mask:0xf bank_mask:0xf
	v_fmac_f32_dpp v235, v51, v123 row_shr:1 row_mask:0xf bank_mask:0xf
; __device__ __forceinline__ unsigned cvt_pk_bf16(float lo, float hi) { unsigned r; asm volatile("v_cvt_pk_bf16_f32 %0, %1, %2" : "=v"(r) : "v"(lo), "v"(hi)); return r; }
; __device__ __forceinline__ float sigmoid_f(float x) { return fast_rcp(1.0f + fast_exp2(-1.4426950409f * x)); }
;     __device__ __forceinline__ void operator()(f32x4 (&acc)[2][2][4][2], const Unit& u, int wr, int wc, int fr, int fq) const {
;     ...
;                     f32x4 cv[2];
; #pragma unroll
;                     for (int bj = 0; bj < 2; ++bj) {
;                         const f32x4 cur = acc[ai][bj][m][n], lo = acc[ai][bj][m > 0 ? m - 1 : 0][n], hi = acc[ai][bj][m < 3 ? m + 1 : 3][n];
;                         f32x4 pv, nv;
; #pragma unroll
;                         for (int idx = 0; idx < 4; ++idx) {
;                             const float y = (fr == 15) ? lo[idx] : cur[idx], z = (fr == 0) ? hi[idx] : cur[idx];
;                             pv[idx] = __int_as_float(__builtin_amdgcn_update_dpp(0, __float_as_int(y), 0x121, 0xf, 0xf, false));
;                             nv[idx] = __int_as_float(__builtin_amdgcn_update_dpp(0, __float_as_int(z), 0x12f, 0xf, 0xf, false));
;                         }
;                         cv[bj] = kc[bj][0] * pv + kc[bj][1] * cur + kc[bj][2] * nv + bc[bj];
;                     }
;                     const int row = row0 + ai * HALF + m * 16;
;                     const bool edge = (m == 0 && fr == 0) || (m == 3 && fr == 15);
;                     if (!edge) { const f32x4 gt = cv[0], vl = cv[1];
;                         u32x2 w; w.x = cvt_pk_bf16(gt[0] * sigmoid_f(gt[0]) * vl[0], gt[1] * sigmoid_f(gt[1]) * vl[1]); w.y = cvt_pk_bf16(gt[2] * sigmoid_f(gt[2]) * vl[2], gt[3] * sigmoid_f(gt[3]) * vl[3]);
;                         *(u32x2*)(ACT + (size_t)row * FF + j4) = w; }
	v_fmac_f32_dpp v236, v52, v124 row_shr:1 row_mask:0xf bank_mask:0xf
	v_fmac_f32_dpp v237, v53, v125 row_shr:1 row_mask:0xf bank_mask:0xf
	v_fmac_f32_dpp v230, v58, v110 row_shl:1 row_mask:0xf bank_mask:0xf
	v_fmac_f32_dpp v231, v59, v111 row_shl:1 row_mask:0xf bank_mask:0xf
	v_fmac_f32_dpp v232, v60, v112 row_shl:1 row_mask:0xf bank_mask:0xf
	v_fmac_f32_dpp v233, v61, v113 row_shl:1 row_mask:0xf bank_mask:0xf
	v_fmac_f32_dpp v234, v50, v102 row_shl:1 row_mask:0xf bank_mask:0xf
	v_fmac_f32_dpp v235, v51, v103 row_shl:1 row_mask:0xf bank_mask:0xf
	v_fmac_f32_dpp v236, v52, v104 row_shl:1 row_mask:0xf bank_mask:0xf
	v_fmac_f32_dpp v237, v53, v105 row_shl:1 row_mask:0xf bank_mask:0xf
	v_fmac_f32_dpp v230, v62, v214 row_ror:1 row_mask:0xf bank_mask:0xf
	v_fmac_f32_dpp v231, v63, v215 row_ror:1 row_mask:0xf bank_mask:0xf
	v_fmac_f32_dpp v232, v64, v216 row_ror:1 row_mask:0xf bank_mask:0xf
	v_fmac_f32_dpp v233, v65, v217 row_ror:1 row_mask:0xf bank_mask:0xf
	v_fmac_f32_dpp v234, v54, v218 row_ror:1 row_mask:0xf bank_mask:0xf
	v_fmac_f32_dpp v235, v55, v219 row_ror:1 row_mask:0xf bank_mask:0xf
	v_fmac_f32_dpp v236, v56, v220 row_ror:1 row_mask:0xf bank_mask:0xf
	v_fmac_f32_dpp v237, v57, v221 row_ror:1 row_mask:0xf bank_mask:0xf
	v_fmac_f32_dpp v230, v46, v222 row_ror:15 row_mask:0xf bank_mask:0xf
	v_fmac_f32_dpp v231, v47, v223 row_ror:15 row_mask:0xf bank_mask:0xf
	v_fmac_f32_dpp v232, v48, v224 row_ror:15 row_mask:0xf bank_mask:0xf
	v_fmac_f32_dpp v233, v49, v225 row_ror:15 row_mask:0xf bank_mask:0xf
	v_fmac_f32_dpp v234, v38, v226 row_ror:15 row_mask:0xf bank_mask:0xf
	v_fmac_f32_dpp v235, v39, v227 row_ror:15 row_mask:0xf bank_mask:0xf
	v_fmac_f32_dpp v236, v40, v228 row_ror:15 row_mask:0xf bank_mask:0xf
	v_fmac_f32_dpp v237, v41, v229 row_ror:15 row_mask:0xf bank_mask:0xf
	v_pk_mul_f32 v[174:175], v[230:231], s[34:35]
	v_pk_mul_f32 v[176:177], v[232:233], s[34:35]
	v_exp_f32_e32 v174, v174
	v_exp_f32_e32 v175, v175
	v_exp_f32_e32 v176, v176
	v_exp_f32_e32 v177, v177
	v_pk_add_f32 v[174:175], v[174:175], s[36:37]
	v_pk_add_f32 v[176:177], v[176:177], s[36:37]
	v_rcp_f32_e32 v174, v174
	v_rcp_f32_e32 v175, v175
	v_rcp_f32_e32 v176, v176
	v_rcp_f32_e32 v177, v177
	v_pk_mul_f32 v[174:175], v[230:231], v[174:175]
	v_pk_mul_f32 v[176:177], v[232:233], v[176:177]
	v_pk_mul_f32 v[174:175], v[174:175], v[234:235]
	v_pk_mul_f32 v[176:177], v[176:177], v[236:237]
	v_cvt_pk_bf16_f32 v136, v174, v175
	v_cvt_pk_bf16_f32 v137, v176, v177
	v_add_u32_e32 v239, 0x2b000, v238
	global_store_dwordx4 v239, v[134:137], s[30:31]
	v_pk_fma_f32 v[230:231], v[46:47], v[118:119], v[106:107]
	v_pk_fma_f32 v[232:233], v[48:49], v[120:121], v[108:109]
	v_pk_fma_f32 v[234:235], v[38:39], v[114:115], v[98:99]
	v_pk_fma_f32 v[236:237], v[40:41], v[116:117], v[100:101]
	v_fmac_f32_dpp v230, v46, v126 row_shr:1 row_mask:0xf bank_mask:0xf
	v_fmac_f32_dpp v231, v47, v127 row_shr:1 row_mask:0xf bank_mask:0xf
	v_fmac_f32_dpp v232, v48, v128 row_shr:1 row_mask:0xf bank_mask:0xf
	v_fmac_f32_dpp v233, v49, v129 row_shr:1 row_mask:0xf bank_mask:0xf
	v_fmac_f32_dpp v234, v38, v122 row_shr:1 row_mask:0xf bank_mask:0xf
	v_fmac_f32_dpp v235, v39, v123 row_shr:1 row_mask:0xf bank_mask:0xf
	v_fmac_f32_dpp v236, v40, v124 row_shr:1 row_mask:0xf bank_mask:0xf
	v_fmac_f32_dpp v237, v41, v125 row_shr:1 row_mask:0xf bank_mask:0xf
	v_fmac_f32_dpp v230, v46, v110 row_shl:1 row_mask:0xf bank_mask:0xf
	v_fmac_f32_dpp v231, v47, v111 row_shl:1 row_mask:0xf bank_mask:0xf
	v_fmac_f32_dpp v232, v48, v112 row_shl:1 row_mask:0xf bank_mask:0xf
	v_fmac_f32_dpp v233, v49, v113 row_shl:1 row_mask:0xf bank_mask:0xf
	v_fmac_f32_dpp v234, v38, v102 row_shl:1 row_mask:0xf bank_mask:0xf
	v_fmac_f32_dpp v235, v39, v103 row_shl:1 row_mask:0xf bank_mask:0xf
	v_fmac_f32_dpp v236, v40, v104 row_shl:1 row_mask:0xf bank_mask:0xf
	v_fmac_f32_dpp v237, v41, v105 row_shl:1 row_mask:0xf bank_mask:0xf
	v_fmac_f32_dpp v230, v58, v214 row_ror:1 row_mask:0xf bank_mask:0xf
	v_fmac_f32_dpp v231, v59, v215 row_ror:1 row_mask:0xf bank_mask:0xf
	v_fmac_f32_dpp v232, v60, v216 row_ror:1 row_mask:0xf bank_mask:0xf
	v_fmac_f32_dpp v233, v61, v217 row_ror:1 row_mask:0xf bank_mask:0xf
	v_fmac_f32_dpp v234, v50, v218 row_ror:1 row_mask:0xf bank_mask:0xf
	v_fmac_f32_dpp v235, v51, v219 row_ror:1 row_mask:0xf bank_mask:0xf
	v_fmac_f32_dpp v236, v52, v220 row_ror:1 row_mask:0xf bank_mask:0xf
	v_fmac_f32_dpp v237, v53, v221 row_ror:1 row_mask:0xf bank_mask:0xf
	v_fmac_f32_dpp v230, v42, v222 row_ror:15 row_mask:0xf bank_mask:0xf
	v_fmac_f32_dpp v231, v43, v223 row_ror:15 row_mask:0xf bank_mask:0xf
	v_fmac_f32_dpp v232, v44, v224 row_ror:15 row_mask:0xf bank_mask:0xf
	v_fmac_f32_dpp v233, v45, v225 row_ror:15 row_mask:0xf bank_mask:0xf
	v_fmac_f32_dpp v234, v34, v226 row_ror:15 row_mask:0xf bank_mask:0xf
	v_fmac_f32_dpp v235, v35, v227 row_ror:15 row_mask:0xf bank_mask:0xf
	v_fmac_f32_dpp v236, v36, v228 row_ror:15 row_mask:0xf bank_mask:0xf
	v_fmac_f32_dpp v237, v37, v229 row_ror:15 row_mask:0xf bank_mask:0xf
	v_pk_mul_f32 v[174:175], v[230:231], s[34:35]
	v_pk_mul_f32 v[176:177], v[232:233], s[34:35]
	v_exp_f32_e32 v174, v174
	v_exp_f32_e32 v175, v175
	v_exp_f32_e32 v176, v176
	v_exp_f32_e32 v177, v177
	v_pk_add_f32 v[174:175], v[174:175], s[36:37]
	v_pk_add_f32 v[176:177], v[176:177], s[36:37]
	v_rcp_f32_e32 v174, v174
	v_rcp_f32_e32 v175, v175
	v_rcp_f32_e32 v176, v176
	v_rcp_f32_e32 v177, v177
	v_pk_mul_f32 v[174:175], v[230:231], v[174:175]
	v_pk_mul_f32 v[176:177], v[232:233], v[176:177]
	v_pk_mul_f32 v[174:175], v[174:175], v[234:235]
	v_pk_mul_f32 v[176:177], v[176:177], v[236:237]
	v_cvt_pk_bf16_f32 v140, v174, v175
; __device__ __forceinline__ unsigned cvt_pk_bf16(float lo, float hi) { unsigned r; asm volatile("v_cvt_pk_bf16_f32 %0, %1, %2" : "=v"(r) : "v"(lo), "v"(hi)); return r; }
; __device__ __forceinline__ float sigmoid_f(float x) { return fast_rcp(1.0f + fast_exp2(-1.4426950409f * x)); }
;     __device__ __forceinline__ void operator()(f32x4 (&acc)[2][2][4][2], const Unit& u, int wr, int wc, int fr, int fq) const {
;     ...
;                 for (int m = 0; m < 4; ++m) {
;                     f32x4 cv[2];
; #pragma unroll
;                     for (int bj = 0; bj < 2; ++bj) {
;                         const f32x4 cur = acc[ai][bj][m][n], lo = acc[ai][bj][m > 0 ? m - 1 : 0][n], hi = acc[ai][bj][m < 3 ? m + 1 : 3][n];
;                         f32x4 pv, nv;
; #pragma unroll
;                         for (int idx = 0; idx < 4; ++idx) {
;                             const float y = (fr == 15) ? lo[idx] : cur[idx], z = (fr == 0) ? hi[idx] : cur[idx];
;                             pv[idx] = __int_as_float(__builtin_amdgcn_update_dpp(0, __float_as_int(y), 0x121, 0xf, 0xf, false));
;                             nv[idx] = __int_as_float(__builtin_amdgcn_update_dpp(0, __float_as_int(z), 0x12f, 0xf, 0xf, false));
;                         }
;                         cv[bj] = kc[bj][0] * pv + kc[bj][1] * cur + kc[bj][2] * nv + bc[bj];
;                     }
;                     const int row = row0 + ai * HALF + m * 16;
;                     const bool edge = (m == 0 && fr == 0) || (m == 3 && fr == 15);
;                     if (!edge) { const f32x4 gt = cv[0], vl = cv[1];
;                         u32x2 w; w.x = cvt_pk_bf16(gt[0] * sigmoid_f(gt[0]) * vl[0], gt[1] * sigmoid_f(gt[1]) * vl[1]); w.y = cvt_pk_bf16(gt[2] * sigmoid_f(gt[2]) * vl[2], gt[3] * sigmoid_f(gt[3]) * vl[3]);
;                         *(u32x2*)(ACT + (size_t)row * FF + j4) = w; }
	v_cvt_pk_bf16_f32 v141, v176, v177
	v_add_u32_e32 v239, 0x56000, v238
	global_store_dwordx4 v239, v[138:141], s[30:31]
	v_pk_fma_f32 v[230:231], v[42:43], v[118:119], v[106:107]
	v_pk_fma_f32 v[232:233], v[44:45], v[120:121], v[108:109]
	v_pk_fma_f32 v[234:235], v[34:35], v[114:115], v[98:99]
	v_pk_fma_f32 v[236:237], v[36:37], v[116:117], v[100:101]
	v_fmac_f32_dpp v230, v42, v126 row_shr:1 row_mask:0xf bank_mask:0xf
	v_fmac_f32_dpp v231, v43, v127 row_shr:1 row_mask:0xf bank_mask:0xf
	v_fmac_f32_dpp v232, v44, v128 row_shr:1 row_mask:0xf bank_mask:0xf
	v_fmac_f32_dpp v233, v45, v129 row_shr:1 row_mask:0xf bank_mask:0xf
	v_fmac_f32_dpp v234, v34, v122 row_shr:1 row_mask:0xf bank_mask:0xf
	v_fmac_f32_dpp v235, v35, v123 row_shr:1 row_mask:0xf bank_mask:0xf
	v_fmac_f32_dpp v236, v36, v124 row_shr:1 row_mask:0xf bank_mask:0xf
	v_fmac_f32_dpp v237, v37, v125 row_shr:1 row_mask:0xf bank_mask:0xf
	v_fmac_f32_dpp v230, v42, v110 row_shl:1 row_mask:0xf bank_mask:0xf
	v_fmac_f32_dpp v231, v43, v111 row_shl:1 row_mask:0xf bank_mask:0xf
	v_fmac_f32_dpp v232, v44, v112 row_shl:1 row_mask:0xf bank_mask:0xf
	v_fmac_f32_dpp v233, v45, v113 row_shl:1 row_mask:0xf bank_mask:0xf
	v_fmac_f32_dpp v234, v34, v102 row_shl:1 row_mask:0xf bank_mask:0xf
	v_fmac_f32_dpp v235, v35, v103 row_shl:1 row_mask:0xf bank_mask:0xf
	v_fmac_f32_dpp v236, v36, v104 row_shl:1 row_mask:0xf bank_mask:0xf
	v_fmac_f32_dpp v237, v37, v105 row_shl:1 row_mask:0xf bank_mask:0xf
	v_fmac_f32_dpp v230, v46, v214 row_ror:1 row_mask:0xf bank_mask:0xf
	v_fmac_f32_dpp v231, v47, v215 row_ror:1 row_mask:0xf bank_mask:0xf
	v_fmac_f32_dpp v232, v48, v216 row_ror:1 row_mask:0xf bank_mask:0xf
	v_fmac_f32_dpp v233, v49, v217 row_ror:1 row_mask:0xf bank_mask:0xf
	v_fmac_f32_dpp v234, v38, v218 row_ror:1 row_mask:0xf bank_mask:0xf
	v_fmac_f32_dpp v235, v39, v219 row_ror:1 row_mask:0xf bank_mask:0xf
	v_fmac_f32_dpp v236, v40, v220 row_ror:1 row_mask:0xf bank_mask:0xf
	v_fmac_f32_dpp v237, v41, v221 row_ror:1 row_mask:0xf bank_mask:0xf
	v_pk_mul_f32 v[174:175], v[230:231], s[34:35]
	v_pk_mul_f32 v[176:177], v[232:233], s[34:35]
	v_exp_f32_e32 v174, v174
	v_exp_f32_e32 v175, v175
	v_exp_f32_e32 v176, v176
	v_exp_f32_e32 v177, v177
	v_pk_add_f32 v[174:175], v[174:175], s[36:37]
	v_pk_add_f32 v[176:177], v[176:177], s[36:37]
	v_rcp_f32_e32 v174, v174
	v_rcp_f32_e32 v175, v175
	v_rcp_f32_e32 v176, v176
	v_rcp_f32_e32 v177, v177
	v_pk_mul_f32 v[174:175], v[230:231], v[174:175]
	v_pk_mul_f32 v[176:177], v[232:233], v[176:177]
	v_pk_mul_f32 v[174:175], v[174:175], v[234:235]
	v_pk_mul_f32 v[176:177], v[176:177], v[236:237]
	v_cvt_pk_bf16_f32 v144, v174, v175
	v_cvt_pk_bf16_f32 v145, v176, v177
	v_add_u32_e32 v239, 0x81000, v238
	s_and_saveexec_b64 s[16:17], s[40:41]
	global_store_dwordx4 v239, v[142:145], s[30:31]
	s_or_b64 exec, exec, s[16:17]
	v_pk_fma_f32 v[230:231], v[30:31], v[118:119], v[106:107]
	v_pk_fma_f32 v[232:233], v[32:33], v[120:121], v[108:109]
	v_pk_fma_f32 v[234:235], v[22:23], v[114:115], v[98:99]
	v_pk_fma_f32 v[236:237], v[24:25], v[116:117], v[100:101]
	v_fmac_f32_dpp v230, v30, v126 row_shr:1 row_mask:0xf bank_mask:0xf
	v_fmac_f32_dpp v231, v31, v127 row_shr:1 row_mask:0xf bank_mask:0xf
	v_fmac_f32_dpp v232, v32, v128 row_shr:1 row_mask:0xf bank_mask:0xf
	v_fmac_f32_dpp v233, v33, v129 row_shr:1 row_mask:0xf bank_mask:0xf
	v_fmac_f32_dpp v234, v22, v122 row_shr:1 row_mask:0xf bank_mask:0xf
	v_fmac_f32_dpp v235, v23, v123 row_shr:1 row_mask:0xf bank_mask:0xf
	v_fmac_f32_dpp v236, v24, v124 row_shr:1 row_mask:0xf bank_mask:0xf
	v_fmac_f32_dpp v237, v25, v125 row_shr:1 row_mask:0xf bank_mask:0xf
	v_fmac_f32_dpp v230, v30, v110 row_shl:1 row_mask:0xf bank_mask:0xf
	v_fmac_f32_dpp v231, v31, v111 row_shl:1 row_mask:0xf bank_mask:0xf
	v_fmac_f32_dpp v232, v32, v112 row_shl:1 row_mask:0xf bank_mask:0xf
	v_fmac_f32_dpp v233, v33, v113 row_shl:1 row_mask:0xf bank_mask:0xf
	v_fmac_f32_dpp v234, v22, v102 row_shl:1 row_mask:0xf bank_mask:0xf
	v_fmac_f32_dpp v235, v23, v103 row_shl:1 row_mask:0xf bank_mask:0xf
	v_fmac_f32_dpp v236, v24, v104 row_shl:1 row_mask:0xf bank_mask:0xf
	v_fmac_f32_dpp v237, v25, v105 row_shl:1 row_mask:0xf bank_mask:0xf
	v_fmac_f32_dpp v230, v26, v222 row_ror:15 row_mask:0xf bank_mask:0xf
	v_fmac_f32_dpp v231, v27, v223 row_ror:15 row_mask:0xf bank_mask:0xf
	v_fmac_f32_dpp v232, v28, v224 row_ror:15 row_mask:0xf bank_mask:0xf
	v_fmac_f32_dpp v233, v29, v225 row_ror:15 row_mask:0xf bank_mask:0xf
	v_fmac_f32_dpp v234, v18, v226 row_ror:15 row_mask:0xf bank_mask:0xf
	v_fmac_f32_dpp v235, v19, v227 row_ror:15 row_mask:0xf bank_mask:0xf
	v_fmac_f32_dpp v236, v20, v228 row_ror:15 row_mask:0xf bank_mask:0xf
	v_fmac_f32_dpp v237, v21, v229 row_ror:15 row_mask:0xf bank_mask:0xf
	v_pk_mul_f32 v[174:175], v[230:231], s[34:35]
	v_pk_mul_f32 v[176:177], v[232:233], s[34:35]
	v_exp_f32_e32 v174, v174
	v_exp_f32_e32 v175, v175
	v_exp_f32_e32 v176, v176
	v_exp_f32_e32 v177, v177
	v_pk_add_f32 v[174:175], v[174:175], s[36:37]
	v_pk_add_f32 v[176:177], v[176:177], s[36:37]
	v_rcp_f32_e32 v174, v174
	v_rcp_f32_e32 v175, v175
	v_rcp_f32_e32 v176, v176
	v_rcp_f32_e32 v177, v177
	v_pk_mul_f32 v[174:175], v[230:231], v[174:175]
	v_pk_mul_f32 v[176:177], v[232:233], v[176:177]
	v_pk_mul_f32 v[174:175], v[174:175], v[234:235]
	v_pk_mul_f32 v[176:177], v[176:177], v[236:237]
	v_cvt_pk_bf16_f32 v180, v174, v175
	v_cvt_pk_bf16_f32 v181, v176, v177
	v_add_u32_e32 v239, 0x158000, v238
	s_and_saveexec_b64 s[16:17], s[44:45]
	global_store_dwordx4 v239, v[178:181], s[30:31]
	s_or_b64 exec, exec, s[16:17]
	v_pk_fma_f32 v[230:231], v[26:27], v[118:119], v[106:107]
	v_pk_fma_f32 v[232:233], v[28:29], v[120:121], v[108:109]
; __device__ __forceinline__ unsigned cvt_pk_bf16(float lo, float hi) { unsigned r; asm volatile("v_cvt_pk_bf16_f32 %0, %1, %2" : "=v"(r) : "v"(lo), "v"(hi)); return r; }
; __device__ __forceinline__ float sigmoid_f(float x) { return fast_rcp(1.0f + fast_exp2(-1.4426950409f * x)); }
;     __device__ __forceinline__ void operator()(f32x4 (&acc)[2][2][4][2], const Unit& u, int wr, int wc, int fr, int fq) const {
;     ...
;                 for (int m = 0; m < 4; ++m) {
;                     f32x4 cv[2];
; #pragma unroll
;                     for (int bj = 0; bj < 2; ++bj) {
;                         const f32x4 cur = acc[ai][bj][m][n], lo = acc[ai][bj][m > 0 ? m - 1 : 0][n], hi = acc[ai][bj][m < 3 ? m + 1 : 3][n];
;                         f32x4 pv, nv;
; #pragma unroll
;                         for (int idx = 0; idx < 4; ++idx) {
;                             const float y = (fr == 15) ? lo[idx] : cur[idx], z = (fr == 0) ? hi[idx] : cur[idx];
;                             pv[idx] = __int_as_float(__builtin_amdgcn_update_dpp(0, __float_as_int(y), 0x121, 0xf, 0xf, false));
;                             nv[idx] = __int_as_float(__builtin_amdgcn_update_dpp(0, __float_as_int(z), 0x12f, 0xf, 0xf, false));
;                         }
;                         cv[bj] = kc[bj][0] * pv + kc[bj][1] * cur + kc[bj][2] * nv + bc[bj];
;                     }
;                     const int row = row0 + ai * HALF + m * 16;
;                     const bool edge = (m == 0 && fr == 0) || (m == 3 && fr == 15);
;                     if (!edge) { const f32x4 gt = cv[0], vl = cv[1];
;                         u32x2 w; w.x = cvt_pk_bf16(gt[0] * sigmoid_f(gt[0]) * vl[0], gt[1] * sigmoid_f(gt[1]) * vl[1]); w.y = cvt_pk_bf16(gt[2] * sigmoid_f(gt[2]) * vl[2], gt[3] * sigmoid_f(gt[3]) * vl[3]);
;                         *(u32x2*)(ACT + (size_t)row * FF + j4) = w; }
	v_pk_fma_f32 v[234:235], v[18:19], v[114:115], v[98:99]
	v_pk_fma_f32 v[236:237], v[20:21], v[116:117], v[100:101]
	v_fmac_f32_dpp v230, v26, v126 row_shr:1 row_mask:0xf bank_mask:0xf
	v_fmac_f32_dpp v231, v27, v127 row_shr:1 row_mask:0xf bank_mask:0xf
	v_fmac_f32_dpp v232, v28, v128 row_shr:1 row_mask:0xf bank_mask:0xf
	v_fmac_f32_dpp v233, v29, v129 row_shr:1 row_mask:0xf bank_mask:0xf
	v_fmac_f32_dpp v234, v18, v122 row_shr:1 row_mask:0xf bank_mask:0xf
	v_fmac_f32_dpp v235, v19, v123 row_shr:1 row_mask:0xf bank_mask:0xf
	v_fmac_f32_dpp v236, v20, v124 row_shr:1 row_mask:0xf bank_mask:0xf
	v_fmac_f32_dpp v237, v21, v125 row_shr:1 row_mask:0xf bank_mask:0xf
	v_fmac_f32_dpp v230, v26, v110 row_shl:1 row_mask:0xf bank_mask:0xf
	v_fmac_f32_dpp v231, v27, v111 row_shl:1 row_mask:0xf bank_mask:0xf
	v_fmac_f32_dpp v232, v28, v112 row_shl:1 row_mask:0xf bank_mask:0xf
	v_fmac_f32_dpp v233, v29, v113 row_shl:1 row_mask:0xf bank_mask:0xf
	v_fmac_f32_dpp v234, v18, v102 row_shl:1 row_mask:0xf bank_mask:0xf
	v_fmac_f32_dpp v235, v19, v103 row_shl:1 row_mask:0xf bank_mask:0xf
	v_fmac_f32_dpp v236, v20, v104 row_shl:1 row_mask:0xf bank_mask:0xf
	v_fmac_f32_dpp v237, v21, v105 row_shl:1 row_mask:0xf bank_mask:0xf
	v_fmac_f32_dpp v230, v30, v214 row_ror:1 row_mask:0xf bank_mask:0xf
	v_fmac_f32_dpp v231, v31, v215 row_ror:1 row_mask:0xf bank_mask:0xf
	v_fmac_f32_dpp v232, v32, v216 row_ror:1 row_mask:0xf bank_mask:0xf
	v_fmac_f32_dpp v233, v33, v217 row_ror:1 row_mask:0xf bank_mask:0xf
	v_fmac_f32_dpp v234, v22, v218 row_ror:1 row_mask:0xf bank_mask:0xf
	v_fmac_f32_dpp v235, v23, v219 row_ror:1 row_mask:0xf bank_mask:0xf
	v_fmac_f32_dpp v236, v24, v220 row_ror:1 row_mask:0xf bank_mask:0xf
	v_fmac_f32_dpp v237, v25, v221 row_ror:1 row_mask:0xf bank_mask:0xf
	v_fmac_f32_dpp v230, v14, v222 row_ror:15 row_mask:0xf bank_mask:0xf
	v_fmac_f32_dpp v231, v15, v223 row_ror:15 row_mask:0xf bank_mask:0xf
	v_fmac_f32_dpp v232, v16, v224 row_ror:15 row_mask:0xf bank_mask:0xf
	v_fmac_f32_dpp v233, v17, v225 row_ror:15 row_mask:0xf bank_mask:0xf
	v_fmac_f32_dpp v234, v6, v226 row_ror:15 row_mask:0xf bank_mask:0xf
	v_fmac_f32_dpp v235, v7, v227 row_ror:15 row_mask:0xf bank_mask:0xf
	v_fmac_f32_dpp v236, v8, v228 row_ror:15 row_mask:0xf bank_mask:0xf
	v_fmac_f32_dpp v237, v9, v229 row_ror:15 row_mask:0xf bank_mask:0xf
	v_pk_mul_f32 v[174:175], v[230:231], s[34:35]
	v_pk_mul_f32 v[176:177], v[232:233], s[34:35]
	v_exp_f32_e32 v174, v174
	v_exp_f32_e32 v175, v175
	v_exp_f32_e32 v176, v176
	v_exp_f32_e32 v177, v177
	v_pk_add_f32 v[174:175], v[174:175], s[36:37]
	v_pk_add_f32 v[176:177], v[176:177], s[36:37]
	v_rcp_f32_e32 v174, v174
	v_rcp_f32_e32 v175, v175
	v_rcp_f32_e32 v176, v176
	v_rcp_f32_e32 v177, v177
	v_pk_mul_f32 v[174:175], v[230:231], v[174:175]
	v_pk_mul_f32 v[176:177], v[232:233], v[176:177]
	v_pk_mul_f32 v[174:175], v[174:175], v[234:235]
	v_pk_mul_f32 v[176:177], v[176:177], v[236:237]
	v_cvt_pk_bf16_f32 v96, v174, v175
	v_cvt_pk_bf16_f32 v97, v176, v177
	v_add_u32_e32 v239, 0x183000, v238
	global_store_dwordx4 v239, v[94:97], s[30:31]
	v_pk_fma_f32 v[230:231], v[14:15], v[118:119], v[106:107]
	v_pk_fma_f32 v[232:233], v[16:17], v[120:121], v[108:109]
	v_pk_fma_f32 v[234:235], v[6:7], v[114:115], v[98:99]
	v_pk_fma_f32 v[236:237], v[8:9], v[116:117], v[100:101]
	v_fmac_f32_dpp v230, v14, v126 row_shr:1 row_mask:0xf bank_mask:0xf
	v_fmac_f32_dpp v231, v15, v127 row_shr:1 row_mask:0xf bank_mask:0xf
	v_fmac_f32_dpp v232, v16, v128 row_shr:1 row_mask:0xf bank_mask:0xf
	v_fmac_f32_dpp v233, v17, v129 row_shr:1 row_mask:0xf bank_mask:0xf
	v_fmac_f32_dpp v234, v6, v122 row_shr:1 row_mask:0xf bank_mask:0xf
	v_fmac_f32_dpp v235, v7, v123 row_shr:1 row_mask:0xf bank_mask:0xf
	v_fmac_f32_dpp v236, v8, v124 row_shr:1 row_mask:0xf bank_mask:0xf
	v_fmac_f32_dpp v237, v9, v125 row_shr:1 row_mask:0xf bank_mask:0xf
	v_fmac_f32_dpp v230, v14, v110 row_shl:1 row_mask:0xf bank_mask:0xf
	v_fmac_f32_dpp v231, v15, v111 row_shl:1 row_mask:0xf bank_mask:0xf
	v_fmac_f32_dpp v232, v16, v112 row_shl:1 row_mask:0xf bank_mask:0xf
	v_fmac_f32_dpp v233, v17, v113 row_shl:1 row_mask:0xf bank_mask:0xf
	v_fmac_f32_dpp v234, v6, v102 row_shl:1 row_mask:0xf bank_mask:0xf
	v_fmac_f32_dpp v235, v7, v103 row_shl:1 row_mask:0xf bank_mask:0xf
	v_fmac_f32_dpp v236, v8, v104 row_shl:1 row_mask:0xf bank_mask:0xf
	v_fmac_f32_dpp v237, v9, v105 row_shl:1 row_mask:0xf bank_mask:0xf
	v_fmac_f32_dpp v230, v26, v214 row_ror:1 row_mask:0xf bank_mask:0xf
	v_fmac_f32_dpp v231, v27, v215 row_ror:1 row_mask:0xf bank_mask:0xf
; __device__ __forceinline__ unsigned cvt_pk_bf16(float lo, float hi) { unsigned r; asm volatile("v_cvt_pk_bf16_f32 %0, %1, %2" : "=v"(r) : "v"(lo), "v"(hi)); return r; }
; __device__ __forceinline__ float sigmoid_f(float x) { return fast_rcp(1.0f + fast_exp2(-1.4426950409f * x)); }
;     __device__ __forceinline__ void operator()(f32x4 (&acc)[2][2][4][2], const Unit& u, int wr, int wc, int fr, int fq) const {
;     ...
;             for (int ai = 0; ai < 2; ++ai) {
;                 const int grp = u.pm * 4 + ai * 2 + wr;
; #pragma unroll
;                 for (int m = 0; m < 4; ++m) {
;                     f32x4 cv[2];
; #pragma unroll
;                     for (int bj = 0; bj < 2; ++bj) {
;                         const f32x4 cur = acc[ai][bj][m][n], lo = acc[ai][bj][m > 0 ? m - 1 : 0][n], hi = acc[ai][bj][m < 3 ? m + 1 : 3][n];
;                         f32x4 pv, nv;
; #pragma unroll
;                         for (int idx = 0; idx < 4; ++idx) {
;                             const float y = (fr == 15) ? lo[idx] : cur[idx], z = (fr == 0) ? hi[idx] : cur[idx];
;                             pv[idx] = __int_as_float(__builtin_amdgcn_update_dpp(0, __float_as_int(y), 0x121, 0xf, 0xf, false));
;                             nv[idx] = __int_as_float(__builtin_amdgcn_update_dpp(0, __float_as_int(z), 0x12f, 0xf, 0xf, false));
;                         }
;                         cv[bj] = kc[bj][0] * pv + kc[bj][1] * cur + kc[bj][2] * nv + bc[bj];
;                     }
;                     const int row = row0 + ai * HALF + m * 16;
;                     const bool edge = (m == 0 && fr == 0) || (m == 3 && fr == 15);
;                     if (!edge) { const f32x4 gt = cv[0], vl = cv[1];
;                         u32x2 w; w.x = cvt_pk_bf16(gt[0] * sigmoid_f(gt[0]) * vl[0], gt[1] * sigmoid_f(gt[1]) * vl[1]); w.y = cvt_pk_bf16(gt[2] * sigmoid_f(gt[2]) * vl[2], gt[3] * sigmoid_f(gt[3]) * vl[3]);
;                         *(u32x2*)(ACT + (size_t)row * FF + j4) = w; }
	v_fmac_f32_dpp v232, v28, v216 row_ror:1 row_mask:0xf bank_mask:0xf
	v_fmac_f32_dpp v233, v29, v217 row_ror:1 row_mask:0xf bank_mask:0xf
	v_fmac_f32_dpp v234, v18, v218 row_ror:1 row_mask:0xf bank_mask:0xf
	v_fmac_f32_dpp v235, v19, v219 row_ror:1 row_mask:0xf bank_mask:0xf
	v_fmac_f32_dpp v236, v20, v220 row_ror:1 row_mask:0xf bank_mask:0xf
	v_fmac_f32_dpp v237, v21, v221 row_ror:1 row_mask:0xf bank_mask:0xf
	v_fmac_f32_dpp v230, v10, v222 row_ror:15 row_mask:0xf bank_mask:0xf
	v_fmac_f32_dpp v231, v11, v223 row_ror:15 row_mask:0xf bank_mask:0xf
	v_fmac_f32_dpp v232, v12, v224 row_ror:15 row_mask:0xf bank_mask:0xf
	v_fmac_f32_dpp v233, v13, v225 row_ror:15 row_mask:0xf bank_mask:0xf
	v_fmac_f32_dpp v234, v2, v226 row_ror:15 row_mask:0xf bank_mask:0xf
	v_fmac_f32_dpp v235, v3, v227 row_ror:15 row_mask:0xf bank_mask:0xf
	v_fmac_f32_dpp v236, v4, v228 row_ror:15 row_mask:0xf bank_mask:0xf
	v_fmac_f32_dpp v237, v5, v229 row_ror:15 row_mask:0xf bank_mask:0xf
	v_pk_mul_f32 v[174:175], v[230:231], s[34:35]
	v_pk_mul_f32 v[176:177], v[232:233], s[34:35]
	v_exp_f32_e32 v174, v174
	v_exp_f32_e32 v175, v175
	v_exp_f32_e32 v176, v176
	v_exp_f32_e32 v177, v177
	v_pk_add_f32 v[174:175], v[174:175], s[36:37]
	v_pk_add_f32 v[176:177], v[176:177], s[36:37]
	v_rcp_f32_e32 v174, v174
	v_rcp_f32_e32 v175, v175
	v_rcp_f32_e32 v176, v176
	v_rcp_f32_e32 v177, v177
	v_pk_mul_f32 v[174:175], v[230:231], v[174:175]
	v_pk_mul_f32 v[176:177], v[232:233], v[176:177]
	v_pk_mul_f32 v[174:175], v[174:175], v[234:235]
	v_pk_mul_f32 v[176:177], v[176:177], v[236:237]
	v_cvt_pk_bf16_f32 v92, v174, v175
	v_cvt_pk_bf16_f32 v93, v176, v177
	v_add_u32_e32 v239, 0x1ae000, v238
	global_store_dwordx4 v239, v[90:93], s[30:31]
	v_pk_fma_f32 v[230:231], v[10:11], v[118:119], v[106:107]
	v_pk_fma_f32 v[232:233], v[12:13], v[120:121], v[108:109]
	v_pk_fma_f32 v[234:235], v[2:3], v[114:115], v[98:99]
	v_pk_fma_f32 v[236:237], v[4:5], v[116:117], v[100:101]
	v_fmac_f32_dpp v230, v10, v126 row_shr:1 row_mask:0xf bank_mask:0xf
	v_fmac_f32_dpp v231, v11, v127 row_shr:1 row_mask:0xf bank_mask:0xf
	v_fmac_f32_dpp v232, v12, v128 row_shr:1 row_mask:0xf bank_mask:0xf
	v_fmac_f32_dpp v233, v13, v129 row_shr:1 row_mask:0xf bank_mask:0xf
	v_fmac_f32_dpp v234, v2, v122 row_shr:1 row_mask:0xf bank_mask:0xf
	v_fmac_f32_dpp v235, v3, v123 row_shr:1 row_mask:0xf bank_mask:0xf
	v_fmac_f32_dpp v236, v4, v124 row_shr:1 row_mask:0xf bank_mask:0xf
	v_fmac_f32_dpp v237, v5, v125 row_shr:1 row_mask:0xf bank_mask:0xf
	v_fmac_f32_dpp v230, v10, v110 row_shl:1 row_mask:0xf bank_mask:0xf
	v_fmac_f32_dpp v231, v11, v111 row_shl:1 row_mask:0xf bank_mask:0xf
	v_fmac_f32_dpp v232, v12, v112 row_shl:1 row_mask:0xf bank_mask:0xf
	v_fmac_f32_dpp v233, v13, v113 row_shl:1 row_mask:0xf bank_mask:0xf
	v_fmac_f32_dpp v234, v2, v102 row_shl:1 row_mask:0xf bank_mask:0xf
	v_fmac_f32_dpp v235, v3, v103 row_shl:1 row_mask:0xf bank_mask:0xf
	v_fmac_f32_dpp v236, v4, v104 row_shl:1 row_mask:0xf bank_mask:0xf
	v_fmac_f32_dpp v237, v5, v105 row_shl:1 row_mask:0xf bank_mask:0xf
	v_fmac_f32_dpp v230, v14, v214 row_ror:1 row_mask:0xf bank_mask:0xf
	v_fmac_f32_dpp v231, v15, v215 row_ror:1 row_mask:0xf bank_mask:0xf
	v_fmac_f32_dpp v232, v16, v216 row_ror:1 row_mask:0xf bank_mask:0xf
	v_fmac_f32_dpp v233, v17, v217 row_ror:1 row_mask:0xf bank_mask:0xf
	v_fmac_f32_dpp v234, v6, v218 row_ror:1 row_mask:0xf bank_mask:0xf
	v_fmac_f32_dpp v235, v7, v219 row_ror:1 row_mask:0xf bank_mask:0xf
	v_fmac_f32_dpp v236, v8, v220 row_ror:1 row_mask:0xf bank_mask:0xf
	v_fmac_f32_dpp v237, v9, v221 row_ror:1 row_mask:0xf bank_mask:0xf
	v_pk_mul_f32 v[174:175], v[230:231], s[34:35]
	v_pk_mul_f32 v[176:177], v[232:233], s[34:35]
	v_exp_f32_e32 v174, v174
	v_exp_f32_e32 v175, v175
	v_exp_f32_e32 v176, v176
	v_exp_f32_e32 v177, v177
	v_pk_add_f32 v[174:175], v[174:175], s[36:37]
	v_pk_add_f32 v[176:177], v[176:177], s[36:37]
	v_rcp_f32_e32 v174, v174
	v_rcp_f32_e32 v175, v175
	v_rcp_f32_e32 v176, v176
	v_rcp_f32_e32 v177, v177
	v_pk_mul_f32 v[174:175], v[230:231], v[174:175]
	v_pk_mul_f32 v[176:177], v[232:233], v[176:177]
	v_pk_mul_f32 v[174:175], v[174:175], v[234:235]
	v_pk_mul_f32 v[176:177], v[176:177], v[236:237]
	v_cvt_pk_bf16_f32 v80, v174, v175
	v_cvt_pk_bf16_f32 v81, v176, v177
	v_add_u32_e32 v239, 0x1d9000, v238
	s_and_saveexec_b64 s[16:17], s[40:41]
	global_store_dwordx4 v239, v[78:81], s[30:31]
	s_or_b64 exec, exec, s[16:17]
	s_movk_i32 s94, 0x1000
	s_movk_i32 s95, 0x3000
	s_and_b64 vcc, exec, s[50:51]
	s_mov_b64 s[12:13], -1
	s_cbranch_vccnz .LBB0_746
